# plus: conv loop + final norm rewritten by hand, P0 rows double-buffered, attention K/V LDS writes moved mid-tile
# speedup vs baseline: 1.0776x; 1.0049x over previous
; #define OPQ int tid = tid0; asm volatile("" : "+v"(tid));
; DEV void norm_item(const Params& p, int l, int g, int item, int tid) {
;   const int wid = tid >> 6, lane = tid & 63;
;   const int r = item * 8 + wid;
;   const int bl = r / NTOK, j = r % NTOK, b = g * G + bl;
;   const float* src;
;   int mrow;
;   if (j < NCTX) {
;     src = (l == 0 ? p.ctx : p.hctx) + ((long)b * NCTX + j) * D;
;     mrow = 32;
;   } else {
;     src = (l == 0 ? p.x : p.out) + ((long)b * SEQ + (j - NCTX)) * D;
;     mrow = b;
;   }
;   const float* md = p.mod + ((long)l * 33 + mrow) * 3072;
;   const float* ng = p.norm_g + l * D;
;   float4 v[4];
;   float ss = 0.f;
; #pragma unroll
;   for (int i = 0; i < 4; ++i) {
;     v[i] = *(const float4*)(src + i * 256 + lane * 4);
;     ss += v[i].x * v[i].x + v[i].y * v[i].y + v[i].z * v[i].z + v[i].w * v[i].w;
;   }
;   ss = wsum(ss, lane);
;   const float rstd = rsqrtf(ss * (1.f / D) + 1e-6f);
; #pragma unroll
;   for (int i = 0; i < 4; ++i) {
;     int col = i * 256 + lane * 4;
;     float4 gg = *(const float4*)(ng + col);
;     float4 sh = *(const float4*)(md + col);
;     float4 sc = *(const float4*)(md + 1024 + col);
;     uint2 o;
;     o.x = pack2(v[i].x * rstd * gg.x * (1.f + sc.x) + sh.x, v[i].y * rstd * gg.y * (1.f + sc.y) + sh.y);
;     o.y = pack2(v[i].z * rstd * gg.z * (1.f + sc.z) + sh.z, v[i].w * rstd * gg.w * (1.f + sc.w) + sh.w);
;     *(uint2*)(p.u + (long)r * D + col) = o;
;   }
; __global__ void __launch_bounds__(512) mega(Params p, int coop) {
;     ...
;         for (int it = bid; it < TG / 8; it += nb) { OPQ norm_item(p, l, g, it, tid); }
.LBB0_104:
	s_cmp_eq_u32 s14, 0
	s_cselect_b64 s[6:7], -1, 0
	v_writelane_b32 v255, s6, 38
	s_lshl_b32 s24, s14, 10
	s_nop 0
	v_writelane_b32 v255, s7, 39
	v_readlane_b32 s6, v253, 23
	v_readlane_b32 s7, v253, 24
	s_andn2_b64 vcc, exec, s[6:7]
	s_cbranch_vccnz .LBB0_111
	v_readlane_b32 s6, v255, 38
	v_readlane_b32 s7, v255, 39
	s_and_b64 s[6:7], s[6:7], exec
	s_cselect_b32 s6, 0, 0x98
	s_cselect_b32 s8, 16, 0xe0
	s_lshl_b64 s[12:13], s[24:25], 2
	v_readlane_b32 s16, v255, 15
	v_readlane_b32 s17, v255, 16
	s_add_u32 s16, s16, s12
	s_mov_b32 s7, s25
	s_mov_b32 s9, s25
	s_mul_i32 s10, s14, 33
	s_mov_b32 s11, s25
	s_addc_u32 s17, s17, s13
	v_readlane_b32 s15, v254, 36
	s_mov_b32 s18, s75
	v_readlane_b32 s12, v253, 0
	v_readlane_b32 s13, v253, 1
	v_lshrrev_b32_e32 v0, 6, v197
	s_load_dwordx2 s[56:57], s[12:13], s6
	s_load_dwordx2 s[58:59], s[12:13], s8
	v_and_b32_e32 v1, 63, v197
	v_readfirstlane_b32 s60, v0
	v_lshlrev_b32_e32 v156, 4, v1
	v_lshlrev_b32_e32 v50, 3, v1
	v_lshlrev_b32_e32 v51, 2, v197
	v_xor_b32_e32 v64, 0x80, v51
	v_and_b32_e32 v64, 0xfc, v64
	v_xor_b32_e32 v65, 0x40, v51
	v_and_b32_e32 v65, 0xfc, v65
	v_xor_b32_e32 v66, 0x20, v51
	v_and_b32_e32 v66, 0xfc, v66
	v_xor_b32_e32 v67, 0x10, v51
	v_and_b32_e32 v67, 0xfc, v67
	v_xor_b32_e32 v68, 0x8, v51
	v_and_b32_e32 v68, 0xfc, v68
	v_xor_b32_e32 v69, 0x4, v51
	v_and_b32_e32 v69, 0xfc, v69
	s_waitcnt lgkmcnt(0)
	s_mov_b32 s46, 0x800000
	s_mov_b64 s[48:49], s[56:57]
	s_mov_b32 s44, 0
	s_cmpk_gt_i32 s18, 0x8ff
	s_cbranch_scc1 .Lp0_skipA_0
	s_mov_b32 s44, 1
	s_add_i32 s19, s15, s60
	s_mul_hi_u32 s32, s19, 0x38e38e39
	s_lshr_b32 s32, s32, 9
	s_mul_i32 s11, s32, 0x900
	s_sub_i32 s61, s19, s11
	s_lshl_b32 s12, s19, 11
	s_add_u32 s12, s86, s12
	s_addc_u32 s13, s87, 0
	v_readlane_b32 s19, v255, 29
	s_nop 0
	s_add_i32 s32, s32, s19
	s_add_i32 s19, s61, 0xffffff00
	s_cmp_lt_u32 s61, 0x100
	s_cselect_b32 s62, s58, s48
	s_cselect_b32 s63, s59, s49
	s_cselect_b32 s11, 20, 23
	s_cselect_b32 s79, 32, s32
	s_cselect_b32 s19, s61, s19
	s_lshl_b32 s32, s32, s11
	s_lshl_b32 s19, s19, 12
	s_add_u32 s32, s32, s19
	s_add_u32 s62, s62, s32
	s_addc_u32 s63, s63, 0
	s_add_i32 s79, s79, s10
	s_mul_i32 s79, s79, 0x3000
	v_readlane_b32 s19, v253, 21
	v_readlane_b32 s32, v253, 22
	s_nop 0
	s_add_u32 s6, s19, s79
	s_addc_u32 s7, s32, 0
	s_add_u32 s8, s6, 0x1000
	s_addc_u32 s9, s7, 0
	global_load_dwordx4 v[4:7], v156, s[62:63]
	global_load_dwordx4 v[8:11], v156, s[62:63] offset:1024
	global_load_dwordx4 v[12:15], v156, s[62:63] offset:2048
	global_load_dwordx4 v[16:19], v156, s[62:63] offset:3072
	global_load_dwordx4 v[200:203], v156, s[8:9]
	global_load_dwordx4 v[96:99], v156, s[16:17]
	global_load_dwordx4 v[174:177], v156, s[6:7]
	global_load_dwordx4 v[204:207], v156, s[8:9] offset:1024
	global_load_dwordx4 v[100:103], v156, s[16:17] offset:1024
	global_load_dwordx4 v[178:181], v156, s[6:7] offset:1024
	global_load_dwordx4 v[208:211], v156, s[8:9] offset:2048
	global_load_dwordx4 v[104:107], v156, s[16:17] offset:2048
	global_load_dwordx4 v[182:185], v156, s[6:7] offset:2048
	global_load_dwordx4 v[212:215], v156, s[8:9] offset:3072
	global_load_dwordx4 v[108:111], v156, s[16:17] offset:3072
	global_load_dwordx4 v[186:189], v156, s[6:7] offset:3072
	v_readlane_b32 s19, v253, 2
	v_readlane_b32 s32, v255, 27
	s_nop 0
	s_add_i32 s18, s18, s19
	s_add_i32 s15, s15, s32
.Lp0_skipA_0:
	s_mov_b32 s45, 0
	s_cmpk_gt_i32 s18, 0x8ff
	s_cbranch_scc1 .Lp0_skipB_1
	s_mov_b32 s45, 1
	s_add_i32 s19, s15, s60
	s_mul_hi_u32 s32, s19, 0x38e38e39
	s_lshr_b32 s32, s32, 9
	s_mul_i32 s11, s32, 0x900
	s_sub_i32 s61, s19, s11
	s_lshl_b32 s54, s19, 11
	s_add_u32 s54, s86, s54
	s_addc_u32 s55, s87, 0
	v_readlane_b32 s19, v255, 29
	s_nop 0
	s_add_i32 s32, s32, s19
	s_add_i32 s19, s61, 0xffffff00
	s_cmp_lt_u32 s61, 0x100
	s_cselect_b32 s56, s58, s48
	s_cselect_b32 s57, s59, s49
	s_cselect_b32 s11, 20, 23
	s_cselect_b32 s79, 32, s32
	s_cselect_b32 s19, s61, s19
	s_lshl_b32 s32, s32, s11
	s_lshl_b32 s19, s19, 12
	s_add_u32 s32, s32, s19
	s_add_u32 s56, s56, s32
	s_addc_u32 s57, s57, 0
	s_add_i32 s79, s79, s10
	s_mul_i32 s79, s79, 0x3000
	v_readlane_b32 s19, v253, 21
	v_readlane_b32 s32, v253, 22
	s_nop 0
	s_add_u32 s50, s19, s79
	s_addc_u32 s51, s32, 0
	s_add_u32 s52, s50, 0x1000
	s_addc_u32 s53, s51, 0
	global_load_dwordx4 v[136:139], v156, s[56:57]
	global_load_dwordx4 v[140:143], v156, s[56:57] offset:1024
	global_load_dwordx4 v[144:147], v156, s[56:57] offset:2048
	global_load_dwordx4 v[148:151], v156, s[56:57] offset:3072
	global_load_dwordx4 v[216:219], v156, s[52:53]
	global_load_dwordx4 v[232:235], v156, s[16:17]
	global_load_dwordx4 v[158:161], v156, s[50:51]
	global_load_dwordx4 v[220:223], v156, s[52:53] offset:1024
	global_load_dwordx4 v[236:239], v156, s[16:17] offset:1024
	global_load_dwordx4 v[162:165], v156, s[50:51] offset:1024
	global_load_dwordx4 v[224:227], v156, s[52:53] offset:2048
	global_load_dwordx4 v[240:243], v156, s[16:17] offset:2048
	global_load_dwordx4 v[166:169], v156, s[50:51] offset:2048
	global_load_dwordx4 v[228:231], v156, s[52:53] offset:3072
	global_load_dwordx4 v[244:247], v156, s[16:17] offset:3072
	global_load_dwordx4 v[170:173], v156, s[50:51] offset:3072
	v_readlane_b32 s19, v253, 2
	v_readlane_b32 s32, v255, 27
	s_nop 0
	s_add_i32 s18, s18, s19
	s_add_i32 s15, s15, s32
.Lp0_skipB_1:
	s_cmp_lg_u32 s45, 0
	s_cbranch_scc0 .Lp0_w0
	s_waitcnt vmcnt(16)
	s_branch .Lp0_x0

; DEV void norm_item(const Params& p, int l, int g, int item, int tid) {
;     ...
;   float ss = 0.f;
; #pragma unroll
;   for (int i = 0; i < 4; ++i) {
;     v[i] = *(const float4*)(src + i * 256 + lane * 4);
;     ss += v[i].x * v[i].x + v[i].y * v[i].y + v[i].z * v[i].z + v[i].w * v[i].w;
;   }
;   ss = wsum(ss, lane);
;   const float rstd = rsqrtf(ss * (1.f / D) + 1e-6f);
; #pragma unroll
;   for (int i = 0; i < 4; ++i) {
;     int col = i * 256 + lane * 4;
;     float4 gg = *(const float4*)(ng + col);
;     float4 sh = *(const float4*)(md + col);
;     float4 sc = *(const float4*)(md + 1024 + col);
;     uint2 o;
;     o.x = pack2(v[i].x * rstd * gg.x * (1.f + sc.x) + sh.x, v[i].y * rstd * gg.y * (1.f + sc.y) + sh.y);
;     o.y = pack2(v[i].z * rstd * gg.z * (1.f + sc.z) + sh.z, v[i].w * rstd * gg.w * (1.f + sc.w) + sh.w);
;     *(uint2*)(p.u + (long)r * D + col) = o;
;   }
.Lp0_x0:
.Lp0_loop:
	v_mov_b32_e32 v40, v5
	v_mov_b32_e32 v41, v9
	v_mov_b32_e32 v38, v4
	v_mov_b32_e32 v39, v8
	v_mov_b32_e32 v48, v13
	v_mov_b32_e32 v49, v17
	v_pk_mul_f32 v[40:41], v[40:41], v[40:41]
	v_mov_b32_e32 v2, v6
	v_mov_b32_e32 v3, v10
	v_mov_b32_e32 v46, v12
	v_mov_b32_e32 v47, v16
	v_pk_mul_f32 v[48:49], v[48:49], v[48:49]
	v_pk_fma_f32 v[38:39], v[38:39], v[38:39], v[40:41]
	v_mov_b32_e32 v36, v7
	v_mov_b32_e32 v37, v11
	v_mov_b32_e32 v42, v14
	v_mov_b32_e32 v43, v18
	v_pk_fma_f32 v[40:41], v[46:47], v[46:47], v[48:49]
	v_pk_fma_f32 v[2:3], v[2:3], v[2:3], v[38:39]
	v_mov_b32_e32 v44, v15
	v_mov_b32_e32 v45, v19
	v_pk_fma_f32 v[38:39], v[42:43], v[42:43], v[40:41]
	v_pk_fma_f32 v[2:3], v[36:37], v[36:37], v[2:3]
	v_pk_fma_f32 v[36:37], v[44:45], v[44:45], v[38:39]
	v_add_f32_e32 v2, v2, v3
	v_add_f32_e32 v2, v2, v36
	v_add_f32_e32 v2, v2, v37
	ds_bpermute_b32 v1, v64, v2
	s_waitcnt lgkmcnt(0)
	v_add_f32_e32 v1, v2, v1
	ds_bpermute_b32 v2, v65, v1
	s_waitcnt lgkmcnt(0)
	v_add_f32_e32 v1, v1, v2
	ds_bpermute_b32 v2, v66, v1
	s_waitcnt lgkmcnt(0)
	v_add_f32_e32 v2, v1, v2
	ds_bpermute_b32 v3, v67, v2
	s_waitcnt lgkmcnt(0)
	v_add_f32_e32 v2, v2, v3
	ds_bpermute_b32 v36, v68, v2
	s_waitcnt lgkmcnt(0)
	v_add_f32_e32 v40, v2, v36
	ds_bpermute_b32 v41, v69, v40
	s_waitcnt lgkmcnt(0)
	v_add_f32_e32 v0, v40, v41
	v_fmamk_f32 v0, v0, 0x3a800000, v196
	v_mul_f32_e32 v1, 0x4b800000, v0
	v_cmp_gt_f32_e32 vcc, s46, v0
	s_nop 1
	v_cndmask_b32_e32 v0, v0, v1, vcc
	v_rsq_f32_e32 v40, v0
	s_nop 0
	v_mul_f32_e32 v20, 0x45800000, v40
	v_cndmask_b32_e32 v40, v40, v20, vcc
	v_pk_add_f32 v[22:23], v[202:203], 1.0 op_sel_hi:[1,0]
	v_pk_add_f32 v[20:21], v[200:201], 1.0 op_sel_hi:[1,0]
	v_pk_mul_f32 v[24:25], v[4:5], v[40:41] op_sel_hi:[1,0]
	v_pk_mul_f32 v[26:27], v[6:7], v[40:41] op_sel_hi:[1,0]
	v_pk_mul_f32 v[24:25], v[96:97], v[24:25]
	v_pk_mul_f32 v[26:27], v[98:99], v[26:27]
	v_pk_fma_f32 v[20:21], v[20:21], v[24:25], v[174:175]
	v_pk_fma_f32 v[22:23], v[22:23], v[26:27], v[176:177]
	v_cvt_pk_bf16_f32 v70, v20, v21
	v_cvt_pk_bf16_f32 v71, v22, v23
	global_store_dwordx2 v50, v[70:71], s[12:13]
	v_pk_mul_f32 v[24:25], v[8:9], v[40:41] op_sel_hi:[1,0]
	v_pk_mul_f32 v[26:27], v[10:11], v[40:41] op_sel_hi:[1,0]
	v_pk_mul_f32 v[24:25], v[24:25], v[100:101]
	v_pk_mul_f32 v[26:27], v[26:27], v[102:103]
	v_pk_add_f32 v[20:21], v[204:205], 1.0 op_sel_hi:[1,0]
	v_pk_add_f32 v[22:23], v[206:207], 1.0 op_sel_hi:[1,0]
	v_pk_fma_f32 v[20:21], v[24:25], v[20:21], v[178:179]
	v_pk_fma_f32 v[22:23], v[26:27], v[22:23], v[180:181]
	v_cvt_pk_bf16_f32 v72, v20, v21
	v_cvt_pk_bf16_f32 v73, v22, v23
	global_store_dwordx2 v50, v[72:73], s[12:13] offset:512
	v_pk_mul_f32 v[24:25], v[12:13], v[40:41] op_sel_hi:[1,0]
	v_pk_mul_f32 v[26:27], v[14:15], v[40:41] op_sel_hi:[1,0]
	v_pk_mul_f32 v[24:25], v[24:25], v[104:105]
	v_pk_mul_f32 v[26:27], v[26:27], v[106:107]
	v_pk_add_f32 v[20:21], v[208:209], 1.0 op_sel_hi:[1,0]
	v_pk_add_f32 v[22:23], v[210:211], 1.0 op_sel_hi:[1,0]
	v_pk_fma_f32 v[20:21], v[24:25], v[20:21], v[182:183]
	v_pk_fma_f32 v[22:23], v[26:27], v[22:23], v[184:185]
	v_cvt_pk_bf16_f32 v74, v20, v21
	v_cvt_pk_bf16_f32 v75, v22, v23
	global_store_dwordx2 v50, v[74:75], s[12:13] offset:1024
	v_pk_mul_f32 v[24:25], v[16:17], v[40:41] op_sel_hi:[1,0]
	v_pk_mul_f32 v[26:27], v[18:19], v[40:41] op_sel_hi:[1,0]
	v_pk_mul_f32 v[24:25], v[24:25], v[108:109]
	v_pk_mul_f32 v[26:27], v[26:27], v[110:111]
	v_pk_add_f32 v[20:21], v[212:213], 1.0 op_sel_hi:[1,0]
	v_pk_add_f32 v[22:23], v[214:215], 1.0 op_sel_hi:[1,0]
	v_pk_fma_f32 v[20:21], v[24:25], v[20:21], v[186:187]
	v_pk_fma_f32 v[22:23], v[26:27], v[22:23], v[188:189]
	v_cvt_pk_bf16_f32 v76, v20, v21
	v_cvt_pk_bf16_f32 v77, v22, v23
	global_store_dwordx2 v50, v[76:77], s[12:13] offset:1536
	s_cmp_lg_u32 s45, 0
	s_cbranch_scc0 .Lp0_done
	s_mov_b32 s44, 0
	s_cmpk_gt_i32 s18, 0x8ff
	s_cbranch_scc1 .Lp0_skipA_2
	s_mov_b32 s44, 1
	s_add_i32 s19, s15, s60
	s_mul_hi_u32 s32, s19, 0x38e38e39
	s_lshr_b32 s32, s32, 9
	s_mul_i32 s11, s32, 0x900
	s_sub_i32 s61, s19, s11
	s_lshl_b32 s12, s19, 11
	s_add_u32 s12, s86, s12
	s_addc_u32 s13, s87, 0
	v_readlane_b32 s19, v255, 29
	s_nop 0
	s_add_i32 s32, s32, s19
	s_add_i32 s19, s61, 0xffffff00
	s_cmp_lt_u32 s61, 0x100
	s_cselect_b32 s62, s58, s48
	s_cselect_b32 s63, s59, s49
	s_cselect_b32 s11, 20, 23
	s_cselect_b32 s79, 32, s32
	s_cselect_b32 s19, s61, s19
	s_lshl_b32 s32, s32, s11
	s_lshl_b32 s19, s19, 12
	s_add_u32 s32, s32, s19
	s_add_u32 s62, s62, s32
	s_addc_u32 s63, s63, 0
	s_add_i32 s79, s79, s10
	s_mul_i32 s79, s79, 0x3000
	v_readlane_b32 s19, v253, 21
	v_readlane_b32 s32, v253, 22
	s_nop 0
	s_add_u32 s6, s19, s79
	s_addc_u32 s7, s32, 0
	s_add_u32 s8, s6, 0x1000
	s_addc_u32 s9, s7, 0
	global_load_dwordx4 v[4:7], v156, s[62:63]
	global_load_dwordx4 v[8:11], v156, s[62:63] offset:1024
	global_load_dwordx4 v[12:15], v156, s[62:63] offset:2048
	global_load_dwordx4 v[16:19], v156, s[62:63] offset:3072
	global_load_dwordx4 v[200:203], v156, s[8:9]
	global_load_dwordx4 v[96:99], v156, s[16:17]
	global_load_dwordx4 v[174:177], v156, s[6:7]
	global_load_dwordx4 v[204:207], v156, s[8:9] offset:1024
	global_load_dwordx4 v[100:103], v156, s[16:17] offset:1024
	global_load_dwordx4 v[178:181], v156, s[6:7] offset:1024
	global_load_dwordx4 v[208:211], v156, s[8:9] offset:2048
	global_load_dwordx4 v[104:107], v156, s[16:17] offset:2048
	global_load_dwordx4 v[182:185], v156, s[6:7] offset:2048
	global_load_dwordx4 v[212:215], v156, s[8:9] offset:3072
	global_load_dwordx4 v[108:111], v156, s[16:17] offset:3072
	global_load_dwordx4 v[186:189], v156, s[6:7] offset:3072
	v_readlane_b32 s19, v253, 2
	v_readlane_b32 s32, v255, 27
	s_nop 0
	s_add_i32 s18, s18, s19
	s_add_i32 s15, s15, s32
; DEV void norm_item(const Params& p, int l, int g, int item, int tid) {
;     ...
;   float ss = 0.f;
; #pragma unroll
;   for (int i = 0; i < 4; ++i) {
;     v[i] = *(const float4*)(src + i * 256 + lane * 4);
;     ss += v[i].x * v[i].x + v[i].y * v[i].y + v[i].z * v[i].z + v[i].w * v[i].w;
;   }
;   ss = wsum(ss, lane);
;   const float rstd = rsqrtf(ss * (1.f / D) + 1e-6f);
; #pragma unroll
;   for (int i = 0; i < 4; ++i) {
;     int col = i * 256 + lane * 4;
;     float4 gg = *(const float4*)(ng + col);
;     float4 sh = *(const float4*)(md + col);
;     float4 sc = *(const float4*)(md + 1024 + col);
;     uint2 o;
;     o.x = pack2(v[i].x * rstd * gg.x * (1.f + sc.x) + sh.x, v[i].y * rstd * gg.y * (1.f + sc.y) + sh.y);
;     o.y = pack2(v[i].z * rstd * gg.z * (1.f + sc.z) + sh.z, v[i].w * rstd * gg.w * (1.f + sc.w) + sh.w);
;     *(uint2*)(p.u + (long)r * D + col) = o;
;   }
.Lp0_skipA_2:
	s_cmp_lg_u32 s44, 0
	s_cbranch_scc0 .Lp0_w1
	s_waitcnt vmcnt(20)
	s_branch .Lp0_x1
.Lp0_w1:
	s_waitcnt vmcnt(4)
.Lp0_x1:
	v_mov_b32_e32 v40, v137
	v_mov_b32_e32 v41, v141
	v_mov_b32_e32 v38, v136
	v_mov_b32_e32 v39, v140
	v_mov_b32_e32 v48, v145
	v_mov_b32_e32 v49, v149
	v_pk_mul_f32 v[40:41], v[40:41], v[40:41]
	v_mov_b32_e32 v2, v138
	v_mov_b32_e32 v3, v142
	v_mov_b32_e32 v46, v144
	v_mov_b32_e32 v47, v148
	v_pk_mul_f32 v[48:49], v[48:49], v[48:49]
	v_pk_fma_f32 v[38:39], v[38:39], v[38:39], v[40:41]
	v_mov_b32_e32 v36, v139
	v_mov_b32_e32 v37, v143
	v_mov_b32_e32 v42, v146
	v_mov_b32_e32 v43, v150
	v_pk_fma_f32 v[40:41], v[46:47], v[46:47], v[48:49]
	v_pk_fma_f32 v[2:3], v[2:3], v[2:3], v[38:39]
	v_mov_b32_e32 v44, v147
	v_mov_b32_e32 v45, v151
	v_pk_fma_f32 v[38:39], v[42:43], v[42:43], v[40:41]
	v_pk_fma_f32 v[2:3], v[36:37], v[36:37], v[2:3]
	v_pk_fma_f32 v[36:37], v[44:45], v[44:45], v[38:39]
	v_add_f32_e32 v2, v2, v3
	v_add_f32_e32 v2, v2, v36
	v_add_f32_e32 v2, v2, v37
	ds_bpermute_b32 v1, v64, v2
	s_waitcnt lgkmcnt(0)
	v_add_f32_e32 v1, v2, v1
	ds_bpermute_b32 v2, v65, v1
	s_waitcnt lgkmcnt(0)
	v_add_f32_e32 v1, v1, v2
	ds_bpermute_b32 v2, v66, v1
	s_waitcnt lgkmcnt(0)
	v_add_f32_e32 v2, v1, v2
	ds_bpermute_b32 v3, v67, v2
	s_waitcnt lgkmcnt(0)
	v_add_f32_e32 v2, v2, v3
	ds_bpermute_b32 v36, v68, v2
	s_waitcnt lgkmcnt(0)
	v_add_f32_e32 v40, v2, v36
	ds_bpermute_b32 v41, v69, v40
	s_waitcnt lgkmcnt(0)
	v_add_f32_e32 v0, v40, v41
	v_fmamk_f32 v0, v0, 0x3a800000, v196
	v_mul_f32_e32 v1, 0x4b800000, v0
	v_cmp_gt_f32_e32 vcc, s46, v0
	s_nop 1
	v_cndmask_b32_e32 v0, v0, v1, vcc
	v_rsq_f32_e32 v40, v0
	s_nop 0
	v_mul_f32_e32 v20, 0x45800000, v40
	v_cndmask_b32_e32 v40, v40, v20, vcc
	v_pk_add_f32 v[22:23], v[218:219], 1.0 op_sel_hi:[1,0]
	v_pk_add_f32 v[20:21], v[216:217], 1.0 op_sel_hi:[1,0]
	v_pk_mul_f32 v[24:25], v[136:137], v[40:41] op_sel_hi:[1,0]
	v_pk_mul_f32 v[26:27], v[138:139], v[40:41] op_sel_hi:[1,0]
	v_pk_mul_f32 v[24:25], v[232:233], v[24:25]
	v_pk_mul_f32 v[26:27], v[234:235], v[26:27]
	v_pk_fma_f32 v[20:21], v[20:21], v[24:25], v[158:159]
	v_pk_fma_f32 v[22:23], v[22:23], v[26:27], v[160:161]
	v_cvt_pk_bf16_f32 v70, v20, v21
	v_cvt_pk_bf16_f32 v71, v22, v23
	global_store_dwordx2 v50, v[70:71], s[54:55]
	v_pk_mul_f32 v[24:25], v[140:141], v[40:41] op_sel_hi:[1,0]
	v_pk_mul_f32 v[26:27], v[142:143], v[40:41] op_sel_hi:[1,0]
	v_pk_mul_f32 v[24:25], v[24:25], v[236:237]
	v_pk_mul_f32 v[26:27], v[26:27], v[238:239]
	v_pk_add_f32 v[20:21], v[220:221], 1.0 op_sel_hi:[1,0]
	v_pk_add_f32 v[22:23], v[222:223], 1.0 op_sel_hi:[1,0]
	v_pk_fma_f32 v[20:21], v[24:25], v[20:21], v[162:163]
	v_pk_fma_f32 v[22:23], v[26:27], v[22:23], v[164:165]
	v_cvt_pk_bf16_f32 v72, v20, v21
	v_cvt_pk_bf16_f32 v73, v22, v23
	global_store_dwordx2 v50, v[72:73], s[54:55] offset:512
	v_pk_mul_f32 v[24:25], v[144:145], v[40:41] op_sel_hi:[1,0]
	v_pk_mul_f32 v[26:27], v[146:147], v[40:41] op_sel_hi:[1,0]
	v_pk_mul_f32 v[24:25], v[24:25], v[240:241]
	v_pk_mul_f32 v[26:27], v[26:27], v[242:243]
	v_pk_add_f32 v[20:21], v[224:225], 1.0 op_sel_hi:[1,0]
	v_pk_add_f32 v[22:23], v[226:227], 1.0 op_sel_hi:[1,0]
	v_pk_fma_f32 v[20:21], v[24:25], v[20:21], v[166:167]
	v_pk_fma_f32 v[22:23], v[26:27], v[22:23], v[168:169]
	v_cvt_pk_bf16_f32 v74, v20, v21
	v_cvt_pk_bf16_f32 v75, v22, v23
	global_store_dwordx2 v50, v[74:75], s[54:55] offset:1024
	v_pk_mul_f32 v[24:25], v[148:149], v[40:41] op_sel_hi:[1,0]
	v_pk_mul_f32 v[26:27], v[150:151], v[40:41] op_sel_hi:[1,0]
	v_pk_mul_f32 v[24:25], v[24:25], v[244:245]
	v_pk_mul_f32 v[26:27], v[26:27], v[246:247]
	v_pk_add_f32 v[20:21], v[228:229], 1.0 op_sel_hi:[1,0]
	v_pk_add_f32 v[22:23], v[230:231], 1.0 op_sel_hi:[1,0]
	v_pk_fma_f32 v[20:21], v[24:25], v[20:21], v[170:171]
	v_pk_fma_f32 v[22:23], v[26:27], v[22:23], v[172:173]
	v_cvt_pk_bf16_f32 v76, v20, v21
	v_cvt_pk_bf16_f32 v77, v22, v23
	global_store_dwordx2 v50, v[76:77], s[54:55] offset:1536
	s_cmp_lg_u32 s44, 0
	s_cbranch_scc0 .Lp0_done
	s_mov_b32 s45, 0
	s_cmpk_gt_i32 s18, 0x8ff
	s_cbranch_scc1 .Lp0_skipB_3
	s_mov_b32 s45, 1
	s_add_i32 s19, s15, s60
	s_mul_hi_u32 s32, s19, 0x38e38e39
	s_lshr_b32 s32, s32, 9
	s_mul_i32 s11, s32, 0x900
	s_sub_i32 s61, s19, s11
	s_lshl_b32 s54, s19, 11
	s_add_u32 s54, s86, s54
	s_addc_u32 s55, s87, 0
	v_readlane_b32 s19, v255, 29
	s_nop 0
	s_add_i32 s32, s32, s19
	s_add_i32 s19, s61, 0xffffff00
	s_cmp_lt_u32 s61, 0x100
	s_cselect_b32 s56, s58, s48
	s_cselect_b32 s57, s59, s49
	s_cselect_b32 s11, 20, 23
	s_cselect_b32 s79, 32, s32
	s_cselect_b32 s19, s61, s19
	s_lshl_b32 s32, s32, s11
	s_lshl_b32 s19, s19, 12
	s_add_u32 s32, s32, s19
	s_add_u32 s56, s56, s32
	s_addc_u32 s57, s57, 0
	s_add_i32 s79, s79, s10
	s_mul_i32 s79, s79, 0x3000
	v_readlane_b32 s19, v253, 21
	v_readlane_b32 s32, v253, 22
	s_nop 0
	s_add_u32 s50, s19, s79
	s_addc_u32 s51, s32, 0
	s_add_u32 s52, s50, 0x1000
	s_addc_u32 s53, s51, 0
	global_load_dwordx4 v[136:139], v156, s[56:57]
	global_load_dwordx4 v[140:143], v156, s[56:57] offset:1024
	global_load_dwordx4 v[144:147], v156, s[56:57] offset:2048
	global_load_dwordx4 v[148:151], v156, s[56:57] offset:3072
	global_load_dwordx4 v[216:219], v156, s[52:53]
	global_load_dwordx4 v[232:235], v156, s[16:17]
	global_load_dwordx4 v[158:161], v156, s[50:51]
	global_load_dwordx4 v[220:223], v156, s[52:53] offset:1024
	global_load_dwordx4 v[236:239], v156, s[16:17] offset:1024
	global_load_dwordx4 v[162:165], v156, s[50:51] offset:1024
	global_load_dwordx4 v[224:227], v156, s[52:53] offset:2048
	global_load_dwordx4 v[240:243], v156, s[16:17] offset:2048
	global_load_dwordx4 v[166:169], v156, s[50:51] offset:2048
	global_load_dwordx4 v[228:231], v156, s[52:53] offset:3072
	global_load_dwordx4 v[244:247], v156, s[16:17] offset:3072
	global_load_dwordx4 v[170:173], v156, s[50:51] offset:3072
	v_readlane_b32 s19, v253, 2
	v_readlane_b32 s32, v255, 27
	s_nop 0
	s_add_i32 s18, s18, s19
	s_add_i32 s15, s15, s32
.Lp0_skipB_3:
	s_cmp_lg_u32 s45, 0
	s_cbranch_scc0 .Lp0_w2
	s_waitcnt vmcnt(20)
	s_branch .Lp0_x2

; DEV void xcd_barrier(const XcdBarrier& b) {
;   asm volatile("s_waitcnt vmcnt(0)" ::: "memory");
;   __syncthreads();
;   if (threadIdx.x == 0) {
;     unsigned* bar = b.bar;
;     __builtin_amdgcn_s_waitcnt(0);
;     unsigned nloc = b.st[0], nx = b.st[1];
;     if (nloc == 0u) { xcd_barrier_complete(bar, b.x, nloc, nx); b.st[0] = nloc; b.st[1] = nx; }
.Lp0_x2:
	s_branch .Lp0_loop
.Lp0_done:
.LBB0_111:
	s_waitcnt vmcnt(0)
	s_barrier
	s_mov_b64 s[6:7], exec
	v_readlane_b32 s8, v253, 4
	v_readlane_b32 s9, v253, 5
	s_and_b64 s[8:9], s[6:7], s[8:9]
	s_mov_b64 exec, s[8:9]
	s_cbranch_execz .LBB0_163
	v_mov_b32_e32 v0, 0x24000
	s_waitcnt vmcnt(0) expcnt(0) lgkmcnt(0)
	ds_read_b32 v2, v0
	v_mov_b32_e32 v0, 0x24004
	ds_read_b32 v0, v0
	s_waitcnt lgkmcnt(1)
	v_cmp_ne_u32_e32 vcc, 0, v2
	s_cbranch_vccnz .LBB0_127
	s_mov_b32 s15, 1
	s_branch .LBB0_115

; DEV void attn_item(const Params& p, int bl, int head, int q0, int nkeys, char* smem, int tid) {
;     ...
;   for (int t = 0; t < nt; ++t) {
;     if (t + 1 < nt) {
; #pragma unroll
;       for (int i = 0; i < 3; ++i) kr[i] = *(const u32x4*)(Kg + (long)(t + 1) * 128 * 96 + (long)(i * 512 + tid) * 8);
; #pragma unroll
;       for (int i = 0; i < 2; ++i) vr[i] = *(const u32x4*)(Vg + (t + 1) * 128 + voffg[i]);
;     }
;     const char* kb = smem + (t & 1) * ASTG;
;     const char* vb = kb + KBYTES;
; #pragma unroll
;     for (int hh = 0; hh < 2; ++hh) {
;       f32x4 s[4][2];
; #pragma unroll
;       for (int kf = 0; kf < 4; ++kf) {
; #pragma unroll
;         for (int ks = 0; ks < 3; ++ks) {
;           bf16x8 a = *(const bf16x8*)(kb + (hh * 64 + kf * 16 + fr) * KROW + ks * 64 + fq * 16);
;           s[kf][0] = __builtin_amdgcn_mfma_f32_16x16x32_bf16(a, qf[0][ks], ks == 0 ? negm[0] : s[kf][0], 0, 0, 0);
;           s[kf][1] = __builtin_amdgcn_mfma_f32_16x16x32_bf16(a, qf[1][ks], ks == 0 ? negm[1] : s[kf][1], 0, 0, 0);
;         }
;       }
; #pragma unroll
;       for (int kk = 0; kk < 2; ++kk) {
;         bf16x8 pb[2];
; #pragma unroll
;         for (int qt = 0; qt < 2; ++qt) {
;           const float e0 = ex2(s[2 * kk][qt][0]), e1 = ex2(s[2 * kk][qt][1]), e2 = ex2(s[2 * kk][qt][2]), e3 = ex2(s[2 * kk][qt][3]);
;           const float e4 = ex2(s[2 * kk + 1][qt][0]), e5 = ex2(s[2 * kk + 1][qt][1]), e6 = ex2(s[2 * kk + 1][qt][2]), e7 = ex2(s[2 * kk + 1][qt][3]);
;           u32x4 cw = {pack2(e0, e1), pack2(e2, e3), pack2(e4, e5), pack2(e6, e7)};
;           pb[qt] = __builtin_bit_cast(bf16x8, cw);
;         }
;         lacc[0] = __builtin_amdgcn_mfma_f32_16x16x32_bf16(ones, pb[0], lacc[0], 0, 0, 0);
;         lacc[1] = __builtin_amdgcn_mfma_f32_16x16x32_bf16(ones, pb[1], lacc[1], 0, 0, 0);
; #pragma unroll
;         for (int dvf = 0; dvf < 4; ++dvf) {
;           const char* vp = vb + (dvf * 16 + fr) * VROW + (hh * 64 + kk * 32 + fq * 4) * 2;
;           const uint2 h0 = *(const uint2*)vp, h1 = *(const uint2*)(vp + 32);
;           u32x4 vw = {h0.x, h0.y, h1.x, h1.y};
;           const bf16x8 va = __builtin_bit_cast(bf16x8, vw);
;           o[dvf][0] = __builtin_amdgcn_mfma_f32_16x16x32_bf16(va, pb[0], o[dvf][0], 0, 0, 0);
;           o[dvf][1] = __builtin_amdgcn_mfma_f32_16x16x32_bf16(va, pb[1], o[dvf][1], 0, 0, 0);
;         }
;       }
;     }
.LBB0_990:
	v_lshl_add_u64 v[248:249], v[168:169], 0, s[6:7]
	v_lshl_add_u64 v[250:251], v[170:171], 0, s[6:7]
	v_lshl_add_u64 v[226:227], v[172:173], 0, s[6:7]
	global_load_dwordx4 v[228:231], v[164:165], off
	global_load_dwordx4 v[232:235], v[166:167], off
	global_load_dwordx4 v[236:239], v[248:249], off
	global_load_dwordx4 v[240:243], v[250:251], off
	global_load_dwordx4 v[244:247], v[226:227], off
	s_add_i32 s9, s13, 1
	s_bitcmp1_b32 s13, 0
	s_cselect_b32 s12, 0xac00, 0
	v_or_b32_e32 v72, s12, v156
	v_add_u32_e32 v179, v72, v178
	ds_read_b128 v[72:75], v179
	ds_read_b128 v[76:79], v179 offset:64
	ds_read_b128 v[84:87], v179 offset:3328
	ds_read_b128 v[92:95], v179 offset:6656
	ds_read_b128 v[96:99], v179 offset:6720
	ds_read_b128 v[104:107], v179 offset:9984
	ds_read_b128 v[112:115], v179 offset:13312
	ds_read_b128 v[152:155], v179 offset:13376
	s_waitcnt lgkmcnt(1)
	v_mfma_f32_16x16x32_bf16 v[180:183], v[112:115], v[12:15], v[24:27]
	s_mov_b32 s78, s76
	s_mov_b32 s79, s76
	v_mfma_f32_16x16x32_bf16 v[184:187], v[112:115], v[20:23], v[28:31]
	ds_read_b128 v[112:115], v179 offset:16640
	s_mov_b32 s77, s76
	s_bitcmp1_b32 s9, 0
	v_mfma_f32_16x16x32_bf16 v[80:83], v[72:75], v[12:15], v[24:27]
	s_mov_b32 s13, s9
	s_cselect_b32 s9, 0xac00, 0
	v_mfma_f32_16x16x32_bf16 v[72:75], v[72:75], v[20:23], v[28:31]
	s_waitcnt lgkmcnt(0)
	v_mfma_f32_16x16x32_bf16 v[198:201], v[112:115], v[12:15], v[24:27]
	v_mfma_f32_16x16x32_bf16 v[202:205], v[112:115], v[20:23], v[28:31]
	ds_read_b128 v[112:115], v179 offset:19968
	ds_read_b128 v[206:209], v179 offset:20032
	v_mfma_f32_16x16x32_bf16 v[88:91], v[84:87], v[12:15], v[24:27]
	v_mfma_f32_16x16x32_bf16 v[84:87], v[84:87], v[20:23], v[28:31]
	s_waitcnt lgkmcnt(1)
	v_mfma_f32_16x16x32_bf16 v[210:213], v[112:115], v[12:15], v[24:27]
	v_mfma_f32_16x16x32_bf16 v[214:217], v[112:115], v[20:23], v[28:31]
	ds_read_b128 v[112:115], v179 offset:23296
	v_mfma_f32_16x16x32_bf16 v[136:139], v[76:79], v[16:19], v[72:75]
	s_nop 2
	ds_read_b128 v[72:75], v179 offset:3392
	ds_read_b128 v[140:143], v179 offset:3456
	v_mfma_f32_16x16x32_bf16 v[108:111], v[104:107], v[12:15], v[24:27]
	v_mfma_f32_16x16x32_bf16 v[104:107], v[104:107], v[20:23], v[28:31]
	s_waitcnt lgkmcnt(1)
	v_mfma_f32_16x16x32_bf16 v[144:147], v[72:75], v[8:11], v[88:91]
	v_mfma_f32_16x16x32_bf16 v[148:151], v[72:75], v[16:19], v[84:87]
	ds_read_b128 v[72:75], v179 offset:10048
	ds_read_b128 v[120:123], v179 offset:10112
	v_mfma_f32_16x16x32_bf16 v[100:103], v[92:95], v[12:15], v[24:27]
	v_mfma_f32_16x16x32_bf16 v[92:95], v[92:95], v[20:23], v[28:31]
	v_mfma_f32_16x16x32_bf16 v[132:135], v[76:79], v[8:11], v[80:83]
	s_waitcnt lgkmcnt(1)
	v_mfma_f32_16x16x32_bf16 v[128:131], v[72:75], v[16:19], v[104:107]
	s_nop 0
	ds_read_b128 v[80:83], v179 offset:16704
	s_nop 0
	ds_read_b128 v[104:107], v179 offset:16768
	v_mfma_f32_16x16x32_bf16 v[116:119], v[96:99], v[16:19], v[92:95]
	v_mfma_f32_16x16x32_bf16 v[124:127], v[72:75], v[8:11], v[108:111]
	v_mfma_f32_16x16x32_bf16 v[76:79], v[152:155], v[8:11], v[180:183]
	v_mfma_f32_16x16x32_bf16 v[72:75], v[152:155], v[16:19], v[184:187]
	s_waitcnt lgkmcnt(1)
	v_mfma_f32_16x16x32_bf16 v[92:95], v[80:83], v[8:11], v[198:201]
	v_mfma_f32_16x16x32_bf16 v[108:111], v[80:83], v[16:19], v[202:205]
	ds_read_b128 v[84:87], v179 offset:23360
	ds_read_b128 v[80:83], v179 offset:23424
	ds_read_b128 v[152:155], v179 offset:128
	s_waitcnt lgkmcnt(0)
	v_mfma_f32_16x16x32_bf16 v[180:183], v[152:155], v[4:7], v[132:135]
	s_nop 2
	ds_read_b128 v[132:135], v179 offset:6784
	v_mfma_f32_16x16x32_bf16 v[218:221], v[112:115], v[12:15], v[24:27]
	v_mfma_f32_16x16x32_bf16 v[222:225], v[112:115], v[20:23], v[28:31]
	v_mfma_f32_16x16x32_bf16 v[112:115], v[96:99], v[8:11], v[100:103]
	v_mfma_f32_16x16x32_bf16 v[152:155], v[152:155], v[0:3], v[136:139]
	v_mfma_f32_16x16x32_bf16 v[136:139], v[140:143], v[0:3], v[148:151]
	s_waitcnt lgkmcnt(0)
	v_mfma_f32_16x16x32_bf16 v[148:151], v[132:135], v[4:7], v[112:115]
	s_nop 3
	ds_read_b128 v[112:115], v179 offset:13440
	v_mfma_f32_16x16x32_bf16 v[132:135], v[132:135], v[0:3], v[116:119]
	v_exp_f32_e32 v139, v139
	s_waitcnt lgkmcnt(0)
	v_mfma_f32_16x16x32_bf16 v[116:119], v[112:115], v[4:7], v[76:79]
	s_nop 4
	v_exp_f32_e32 v132, v132
	v_exp_f32_e32 v133, v133
	v_exp_f32_e32 v134, v134
	v_mfma_f32_16x16x32_bf16 v[112:115], v[112:115], v[0:3], v[72:75]
	s_nop 2
	ds_read_b128 v[184:187], v179 offset:20096
	v_exp_f32_e32 v135, v135
	v_mfma_f32_16x16x32_bf16 v[100:103], v[206:209], v[8:11], v[210:213]
	v_exp_f32_e32 v112, v112
	v_exp_f32_e32 v113, v113
	v_exp_f32_e32 v114, v114
	v_mfma_f32_16x16x32_bf16 v[96:99], v[206:209], v[16:19], v[214:217]
	v_exp_f32_e32 v115, v115
	v_exp_f32_e32 v116, v116
	v_exp_f32_e32 v117, v117
	v_mfma_f32_16x16x32_bf16 v[88:91], v[84:87], v[8:11], v[218:221]
	v_exp_f32_e32 v118, v118
	v_exp_f32_e32 v119, v119
	v_lshl_add_u64 v[164:165], v[164:165], 0, s[26:27]
	v_mfma_f32_16x16x32_bf16 v[84:87], v[84:87], v[16:19], v[222:225]
	v_lshl_add_u64 v[166:167], v[166:167], 0, s[26:27]
	v_mfma_f32_16x16x32_bf16 v[144:147], v[140:143], v[4:7], v[144:147]
	v_mfma_f32_16x16x32_bf16 v[140:143], v[120:123], v[4:7], v[124:127]
	v_mfma_f32_16x16x32_bf16 v[124:127], v[120:123], v[0:3], v[128:131]
	s_nop 2
	v_mfma_f32_16x16x32_bf16 v[120:123], v[104:107], v[4:7], v[92:95]
	s_nop 1
	v_exp_f32_e32 v140, v140
	v_exp_f32_e32 v141, v141
	v_exp_f32_e32 v142, v142
	s_waitcnt lgkmcnt(0)
	v_add_u32_e32 v191, s9, v159
	v_add_u32_e32 v192, s9, v161
	v_add_u32_e32 v193, s9, v163
	v_add_u32_e32 v194, s9, v160
	v_add_u32_e32 v195, s9, v162
	s_waitcnt vmcnt(0)
; DEV float ex2(float x) { return __builtin_amdgcn_exp2f(x); }
; DEV void attn_item(const Params& p, int bl, int head, int q0, int nkeys, char* smem, int tid) {
;     ...
;       for (int kk = 0; kk < 2; ++kk) {
;         bf16x8 pb[2];
; #pragma unroll
;         for (int qt = 0; qt < 2; ++qt) {
;           const float e0 = ex2(s[2 * kk][qt][0]), e1 = ex2(s[2 * kk][qt][1]), e2 = ex2(s[2 * kk][qt][2]), e3 = ex2(s[2 * kk][qt][3]);
;           const float e4 = ex2(s[2 * kk + 1][qt][0]), e5 = ex2(s[2 * kk + 1][qt][1]), e6 = ex2(s[2 * kk + 1][qt][2]), e7 = ex2(s[2 * kk + 1][qt][3]);
;           u32x4 cw = {pack2(e0, e1), pack2(e2, e3), pack2(e4, e5), pack2(e6, e7)};
;           pb[qt] = __builtin_bit_cast(bf16x8, cw);
;         }
;         lacc[0] = __builtin_amdgcn_mfma_f32_16x16x32_bf16(ones, pb[0], lacc[0], 0, 0, 0);
;         lacc[1] = __builtin_amdgcn_mfma_f32_16x16x32_bf16(ones, pb[1], lacc[1], 0, 0, 0);
; #pragma unroll
;         for (int dvf = 0; dvf < 4; ++dvf) {
;           const char* vp = vb + (dvf * 16 + fr) * VROW + (hh * 64 + kk * 32 + fq * 4) * 2;
;           const uint2 h0 = *(const uint2*)vp, h1 = *(const uint2*)(vp + 32);
;           u32x4 vw = {h0.x, h0.y, h1.x, h1.y};
;           const bf16x8 va = __builtin_bit_cast(bf16x8, vw);
;           o[dvf][0] = __builtin_amdgcn_mfma_f32_16x16x32_bf16(va, pb[0], o[dvf][0], 0, 0, 0);
;           o[dvf][1] = __builtin_amdgcn_mfma_f32_16x16x32_bf16(va, pb[1], o[dvf][1], 0, 0, 0);
;         }
;       }
;     }
;     if (t + 1 < nt) {
;       char* nb = smem + ((t + 1) & 1) * ASTG;
; #pragma unroll
;       for (int i = 0; i < 3; ++i) *(u32x4*)(nb + koff[i]) = kr[i];
; #pragma unroll
;       for (int i = 0; i < 2; ++i) *(u32x4*)(nb + KBYTES + voffl[i]) = vr[i];
	ds_write_b128 v191, v[236:239]
	ds_write_b128 v192, v[240:243]
	ds_write_b128 v193, v[244:247]
	ds_write_b128 v194, v[228:231] offset:26624
	ds_write_b128 v195, v[232:235] offset:26624
	v_mfma_f32_16x16x32_bf16 v[198:201], v[184:187], v[4:7], v[100:103]
	v_exp_f32_e32 v143, v143
	v_exp_f32_e32 v127, v127
	v_exp_f32_e32 v120, v120
	v_or_b32_e32 v130, s12, v176
	v_add_u32_e32 v130, v130, v177
	v_add_u32_e32 v179, 0x6800, v130
	v_mfma_f32_16x16x32_bf16 v[96:99], v[184:187], v[0:3], v[96:99]
	v_add_u32_e32 v188, 0x7800, v130
	v_add_u32_e32 v189, 0x8800, v130
	v_add_u32_e32 v190, 0x9800, v130
	v_mfma_f32_16x16x32_bf16 v[88:91], v[80:83], v[4:7], v[88:91]
	ds_read2_b64 v[184:187], v179 offset1:4
	v_exp_f32_e32 v130, v144
	v_exp_f32_e32 v131, v145
	v_mfma_f32_16x16x32_bf16 v[80:83], v[80:83], v[0:3], v[84:87]
	v_exp_f32_e32 v144, v146
	v_exp_f32_e32 v145, v147
	v_exp_f32_e32 v146, v152
	v_exp_f32_e32 v84, v180
	v_exp_f32_e32 v85, v181
	v_exp_f32_e32 v86, v182
	v_exp_f32_e32 v87, v183
	v_exp_f32_e32 v147, v153
	v_exp_f32_e32 v152, v154
	v_exp_f32_e32 v153, v155
	v_exp_f32_e32 v154, v136
	v_exp_f32_e32 v155, v137
	v_exp_f32_e32 v180, v138
	v_cvt_pk_bf16_f32 v84, v84, v85
	v_cvt_pk_bf16_f32 v85, v86, v87
	v_cvt_pk_bf16_f32 v87, v144, v145
	v_cvt_pk_bf16_f32 v136, v146, v147
	ds_read2_b64 v[144:147], v188 offset0:32 offset1:36
	v_mfma_f32_16x16x32_bf16 v[108:111], v[104:107], v[0:3], v[108:111]
	v_mov_b64_e32 v[106:107], s[78:79]
	v_mov_b64_e32 v[104:105], s[76:77]
	v_cvt_pk_bf16_f32 v86, v130, v131
	v_cvt_pk_bf16_f32 v137, v152, v153
	v_cvt_pk_bf16_f32 v138, v154, v155
	v_cvt_pk_bf16_f32 v139, v180, v139
	s_waitcnt lgkmcnt(1)
	v_mfma_f32_16x16x32_bf16 v[32:35], v[184:187], v[84:87], v[32:35]
	v_exp_f32_e32 v130, v148
	v_exp_f32_e32 v131, v149
	v_exp_f32_e32 v148, v126
	v_mfma_f32_16x16x32_bf16 v[36:39], v[184:187], v[136:139], v[36:39]
	ds_read2_b64 v[152:155], v189 offset0:64 offset1:68
	ds_read2_b64 v[180:183], v190 offset0:96 offset1:100
	ds_read2_b64 v[184:187], v179 offset0:8 offset1:12
	v_exp_f32_e32 v121, v121
	v_cvt_pk_bf16_f32 v127, v148, v127
	s_waitcnt lgkmcnt(3)
	v_mfma_f32_16x16x32_bf16 v[40:43], v[144:147], v[84:87], v[40:43]
	v_exp_f32_e32 v122, v122
	v_exp_f32_e32 v123, v123
	v_exp_f32_e32 v96, v96
	v_mfma_f32_16x16x32_bf16 v[60:63], v[144:147], v[136:139], v[60:63]
	v_exp_f32_e32 v146, v124
	v_cvt_pk_bf16_f32 v124, v132, v133
	v_exp_f32_e32 v144, v150
	s_waitcnt lgkmcnt(2)
	v_mfma_f32_16x16x32_bf16 v[44:47], v[152:155], v[84:87], v[44:47]
	v_exp_f32_e32 v145, v151
	v_exp_f32_e32 v147, v125
	v_cvt_pk_bf16_f32 v125, v134, v135
	s_waitcnt lgkmcnt(1)
	v_mfma_f32_16x16x32_bf16 v[48:51], v[180:183], v[84:87], v[48:51]
	v_exp_f32_e32 v97, v97
	v_cvt_pk_bf16_f32 v126, v146, v147
	v_exp_f32_e32 v98, v98
	v_mfma_f32_16x16x32_bf16 v[68:71], v[104:107], v[84:87], v[68:71]
	v_cvt_pk_bf16_f32 v84, v130, v131
	ds_read2_b64 v[130:133], v188 offset0:40 offset1:44
	v_cvt_pk_bf16_f32 v85, v144, v145
	v_cvt_pk_bf16_f32 v86, v140, v141
	v_cvt_pk_bf16_f32 v87, v142, v143
	v_mfma_f32_16x16x32_bf16 v[64:67], v[152:155], v[136:139], v[64:67]
	v_exp_f32_e32 v99, v99
	v_exp_f32_e32 v111, v111
	v_mfma_f32_16x16x32_bf16 v[52:55], v[180:183], v[136:139], v[52:55]
	v_exp_f32_e32 v88, v88
	v_exp_f32_e32 v89, v89
	v_exp_f32_e32 v90, v90
	v_mfma_f32_16x16x32_bf16 v[56:59], v[104:107], v[136:139], v[56:59]
	ds_read2_b64 v[134:137], v189 offset0:72 offset1:76
	ds_read2_b64 v[138:141], v190 offset0:104 offset1:108
	ds_read2_b64 v[142:145], v179 offset0:16 offset1:20
	v_exp_f32_e32 v91, v91
	s_add_u32 s6, s6, 0x6000
	s_waitcnt lgkmcnt(3)
	v_mfma_f32_16x16x32_bf16 v[40:43], v[130:133], v[84:87], v[40:43]
	s_addc_u32 s7, s7, 0
	s_cmp_eq_u32 s6, 0x66000
	v_mfma_f32_16x16x32_bf16 v[60:63], v[130:133], v[124:127], v[60:63]
	v_exp_f32_e32 v130, v108
	v_exp_f32_e32 v131, v109
	v_cvt_pk_bf16_f32 v108, v112, v113
	v_cvt_pk_bf16_f32 v109, v114, v115
	ds_read2_b64 v[112:115], v188 offset0:48 offset1:52
	v_mfma_f32_16x16x32_bf16 v[32:35], v[184:187], v[84:87], v[32:35]
	v_exp_f32_e32 v132, v110
	v_cvt_pk_bf16_f32 v110, v130, v131
	v_cvt_pk_bf16_f32 v111, v132, v111
	v_mfma_f32_16x16x32_bf16 v[36:39], v[184:187], v[124:127], v[36:39]
	s_waitcnt lgkmcnt(3)
	v_mfma_f32_16x16x32_bf16 v[44:47], v[134:137], v[84:87], v[44:47]
	v_mfma_f32_16x16x32_bf16 v[64:67], v[134:137], v[124:127], v[64:67]
	s_waitcnt lgkmcnt(2)
	v_mfma_f32_16x16x32_bf16 v[48:51], v[138:141], v[84:87], v[48:51]
	v_mfma_f32_16x16x32_bf16 v[52:55], v[138:141], v[124:127], v[52:55]
	v_mfma_f32_16x16x32_bf16 v[68:71], v[104:107], v[84:87], v[68:71]
	v_cvt_pk_bf16_f32 v84, v116, v117
	v_cvt_pk_bf16_f32 v85, v118, v119
	v_cvt_pk_bf16_f32 v86, v120, v121
	v_mfma_f32_16x16x32_bf16 v[56:59], v[104:107], v[124:127], v[56:59]
	v_cvt_pk_bf16_f32 v87, v122, v123
	ds_read2_b64 v[116:119], v189 offset0:80 offset1:84
	ds_read2_b64 v[120:123], v190 offset0:112 offset1:116
	ds_read2_b64 v[124:127], v179 offset0:24 offset1:28
	s_waitcnt lgkmcnt(4)
	v_mfma_f32_16x16x32_bf16 v[32:35], v[142:145], v[84:87], v[32:35]
	s_waitcnt lgkmcnt(3)
	v_mfma_f32_16x16x32_bf16 v[40:43], v[112:115], v[84:87], v[40:43]
	s_waitcnt lgkmcnt(2)
	v_mfma_f32_16x16x32_bf16 v[44:47], v[116:119], v[84:87], v[44:47]
	s_waitcnt lgkmcnt(1)
	v_mfma_f32_16x16x32_bf16 v[48:51], v[120:123], v[84:87], v[48:51]
	v_mfma_f32_16x16x32_bf16 v[68:71], v[104:107], v[84:87], v[68:71]
	v_cvt_pk_bf16_f32 v84, v96, v97
	v_cvt_pk_bf16_f32 v85, v98, v99
	v_mfma_f32_16x16x32_bf16 v[64:67], v[116:119], v[108:111], v[64:67]
	v_exp_f32_e32 v118, v82
	v_exp_f32_e32 v87, v83
	v_cvt_pk_bf16_f32 v82, v88, v89
	v_cvt_pk_bf16_f32 v83, v90, v91
	ds_read2_b64 v[88:91], v188 offset0:56 offset1:60
	v_mfma_f32_16x16x32_bf16 v[60:63], v[112:115], v[108:111], v[60:63]
	v_exp_f32_e32 v112, v198
	v_exp_f32_e32 v113, v199
	v_exp_f32_e32 v114, v200
	v_exp_f32_e32 v115, v201
	v_exp_f32_e32 v116, v80
	v_exp_f32_e32 v117, v81
	v_cvt_pk_bf16_f32 v80, v112, v113
	v_cvt_pk_bf16_f32 v81, v114, v115
	v_cvt_pk_bf16_f32 v87, v118, v87
	v_cvt_pk_bf16_f32 v86, v116, v117
	s_waitcnt lgkmcnt(0)
; DEV float ex2(float x) { return __builtin_amdgcn_exp2f(x); }
; DEV void attn_item(const Params& p, int bl, int head, int q0, int nkeys, char* smem, int tid) {
;     ...
;     for (int hh = 0; hh < 2; ++hh) {
;       f32x4 s[4][2];
; #pragma unroll
;       for (int kf = 0; kf < 4; ++kf) {
; #pragma unroll
;         for (int ks = 0; ks < 3; ++ks) {
;           bf16x8 a = *(const bf16x8*)(kb + (hh * 64 + kf * 16 + fr) * KROW + ks * 64 + fq * 16);
;           s[kf][0] = __builtin_amdgcn_mfma_f32_16x16x32_bf16(a, qf[0][ks], ks == 0 ? negm[0] : s[kf][0], 0, 0, 0);
;           s[kf][1] = __builtin_amdgcn_mfma_f32_16x16x32_bf16(a, qf[1][ks], ks == 0 ? negm[1] : s[kf][1], 0, 0, 0);
;         }
;       }
; #pragma unroll
;       for (int kk = 0; kk < 2; ++kk) {
;         bf16x8 pb[2];
; #pragma unroll
;         for (int qt = 0; qt < 2; ++qt) {
;           const float e0 = ex2(s[2 * kk][qt][0]), e1 = ex2(s[2 * kk][qt][1]), e2 = ex2(s[2 * kk][qt][2]), e3 = ex2(s[2 * kk][qt][3]);
;           const float e4 = ex2(s[2 * kk + 1][qt][0]), e5 = ex2(s[2 * kk + 1][qt][1]), e6 = ex2(s[2 * kk + 1][qt][2]), e7 = ex2(s[2 * kk + 1][qt][3]);
;           u32x4 cw = {pack2(e0, e1), pack2(e2, e3), pack2(e4, e5), pack2(e6, e7)};
;           pb[qt] = __builtin_bit_cast(bf16x8, cw);
;         }
;         lacc[0] = __builtin_amdgcn_mfma_f32_16x16x32_bf16(ones, pb[0], lacc[0], 0, 0, 0);
;         lacc[1] = __builtin_amdgcn_mfma_f32_16x16x32_bf16(ones, pb[1], lacc[1], 0, 0, 0);
; #pragma unroll
;         for (int dvf = 0; dvf < 4; ++dvf) {
;           const char* vp = vb + (dvf * 16 + fr) * VROW + (hh * 64 + kk * 32 + fq * 4) * 2;
;           const uint2 h0 = *(const uint2*)vp, h1 = *(const uint2*)(vp + 32);
;           u32x4 vw = {h0.x, h0.y, h1.x, h1.y};
;           const bf16x8 va = __builtin_bit_cast(bf16x8, vw);
;           o[dvf][0] = __builtin_amdgcn_mfma_f32_16x16x32_bf16(va, pb[0], o[dvf][0], 0, 0, 0);
;           o[dvf][1] = __builtin_amdgcn_mfma_f32_16x16x32_bf16(va, pb[1], o[dvf][1], 0, 0, 0);
;         }
;       }
;     }
;     if (t + 1 < nt) {
;       char* nb = smem + ((t + 1) & 1) * ASTG;
; #pragma unroll
;       for (int i = 0; i < 3; ++i) *(u32x4*)(nb + koff[i]) = kr[i];
; #pragma unroll
;       for (int i = 0; i < 2; ++i) *(u32x4*)(nb + KBYTES + voffl[i]) = vr[i];
;     }
;     __syncthreads();
	v_mfma_f32_16x16x32_bf16 v[40:43], v[88:91], v[80:83], v[40:43]
	v_mfma_f32_16x16x32_bf16 v[60:63], v[88:91], v[84:87], v[60:63]
	ds_read2_b64 v[88:91], v189 offset0:88 offset1:92
	s_waitcnt lgkmcnt(0)
	v_mfma_f32_16x16x32_bf16 v[44:47], v[88:91], v[80:83], v[44:47]
	v_mfma_f32_16x16x32_bf16 v[64:67], v[88:91], v[84:87], v[64:67]
	ds_read2_b64 v[88:91], v190 offset0:120 offset1:124
	v_mfma_f32_16x16x32_bf16 v[36:39], v[142:145], v[108:111], v[36:39]
	v_mfma_f32_16x16x32_bf16 v[52:55], v[120:123], v[108:111], v[52:55]
	v_mfma_f32_16x16x32_bf16 v[56:59], v[104:107], v[108:111], v[56:59]
	v_mfma_f32_16x16x32_bf16 v[32:35], v[124:127], v[80:83], v[32:35]
	v_mfma_f32_16x16x32_bf16 v[36:39], v[124:127], v[84:87], v[36:39]
	s_waitcnt lgkmcnt(0)
	v_mfma_f32_16x16x32_bf16 v[48:51], v[88:91], v[80:83], v[48:51]
	v_mfma_f32_16x16x32_bf16 v[52:55], v[88:91], v[84:87], v[52:55]
	v_mfma_f32_16x16x32_bf16 v[68:71], v[104:107], v[80:83], v[68:71]
	v_mfma_f32_16x16x32_bf16 v[56:59], v[104:107], v[84:87], v[56:59]
	s_waitcnt lgkmcnt(0)
	s_barrier
	s_cbranch_scc0 .LBB0_990
	v_add3_u32 v108, s9, v156, v178
	ds_read_b128 v[72:75], v108
	ds_read_b128 v[80:83], v108 offset:64
	s_ashr_i32 s6, s11, 3
	s_ashr_i32 s7, s6, 31
	s_waitcnt lgkmcnt(1)
	v_mfma_f32_16x16x32_bf16 v[76:79], v[72:75], v[12:15], v[24:27]
	ds_read_b128 v[88:91], v108 offset:3392
	ds_read_b128 v[96:99], v108 offset:6720
	ds_read_b128 v[104:107], v108 offset:10048
	v_mfma_f32_16x16x32_bf16 v[72:75], v[72:75], v[20:23], v[28:31]
	s_waitcnt lgkmcnt(3)
	v_mfma_f32_16x16x32_bf16 v[76:79], v[80:83], v[8:11], v[76:79]
	v_mfma_f32_16x16x32_bf16 v[72:75], v[80:83], v[16:19], v[72:75]
	ds_read_b128 v[80:83], v108 offset:128
	s_waitcnt lgkmcnt(0)
	v_mfma_f32_16x16x32_bf16 v[76:79], v[80:83], v[4:7], v[76:79]
	s_nop 7
	v_exp_f32_e32 v76, v76
	v_mfma_f32_16x16x32_bf16 v[72:75], v[80:83], v[0:3], v[72:75]
	ds_read_b128 v[80:83], v108 offset:3328
	v_exp_f32_e32 v77, v77
	v_exp_f32_e32 v78, v78
	s_waitcnt lgkmcnt(0)
	v_mfma_f32_16x16x32_bf16 v[84:87], v[80:83], v[12:15], v[24:27]
	v_exp_f32_e32 v79, v79
	v_cvt_pk_bf16_f32 v76, v76, v77
	s_nop 0
	v_exp_f32_e32 v72, v72
	v_mfma_f32_16x16x32_bf16 v[80:83], v[80:83], v[20:23], v[28:31]
	v_cvt_pk_bf16_f32 v77, v78, v79
	v_exp_f32_e32 v73, v73
	v_exp_f32_e32 v74, v74
	v_mfma_f32_16x16x32_bf16 v[84:87], v[88:91], v[8:11], v[84:87]
	v_exp_f32_e32 v75, v75
	v_cvt_pk_bf16_f32 v72, v72, v73
	v_cvt_pk_bf16_f32 v73, v74, v75
	v_mfma_f32_16x16x32_bf16 v[80:83], v[88:91], v[16:19], v[80:83]
	ds_read_b128 v[88:91], v108 offset:3456
	s_waitcnt lgkmcnt(0)
	v_mfma_f32_16x16x32_bf16 v[84:87], v[88:91], v[4:7], v[84:87]
	s_nop 7
	v_exp_f32_e32 v84, v84
	v_mfma_f32_16x16x32_bf16 v[80:83], v[88:91], v[0:3], v[80:83]
	ds_read_b128 v[88:91], v108 offset:6656
	v_exp_f32_e32 v85, v85
	v_exp_f32_e32 v86, v86
	s_waitcnt lgkmcnt(0)
	v_mfma_f32_16x16x32_bf16 v[92:95], v[88:91], v[12:15], v[24:27]
	v_exp_f32_e32 v87, v87
	v_cvt_pk_bf16_f32 v78, v84, v85
	s_nop 0
	v_exp_f32_e32 v109, v82
	v_mfma_f32_16x16x32_bf16 v[88:91], v[88:91], v[20:23], v[28:31]
	v_cvt_pk_bf16_f32 v79, v86, v87
	v_exp_f32_e32 v110, v83
	v_mfma_f32_16x16x32_bf16 v[92:95], v[96:99], v[8:11], v[92:95]
	v_cvt_pk_bf16_f32 v75, v109, v110
	v_mfma_f32_16x16x32_bf16 v[88:91], v[96:99], v[16:19], v[88:91]
	ds_read_b128 v[96:99], v108 offset:6784
	s_waitcnt lgkmcnt(0)
	v_mfma_f32_16x16x32_bf16 v[92:95], v[96:99], v[4:7], v[92:95]
	v_mfma_f32_16x16x32_bf16 v[88:91], v[96:99], v[0:3], v[88:91]
	ds_read_b128 v[96:99], v108 offset:9984
	s_waitcnt lgkmcnt(0)
	v_mfma_f32_16x16x32_bf16 v[100:103], v[96:99], v[12:15], v[24:27]
	v_mfma_f32_16x16x32_bf16 v[96:99], v[96:99], v[20:23], v[28:31]
	v_mfma_f32_16x16x32_bf16 v[100:103], v[104:107], v[8:11], v[100:103]
	v_mfma_f32_16x16x32_bf16 v[96:99], v[104:107], v[16:19], v[96:99]
	ds_read_b128 v[104:107], v108 offset:10112
	s_waitcnt lgkmcnt(0)
	v_mfma_f32_16x16x32_bf16 v[100:103], v[104:107], v[4:7], v[100:103]
	v_mfma_f32_16x16x32_bf16 v[96:99], v[104:107], v[0:3], v[96:99]
	v_add3_u32 v104, s9, v176, v177
	v_add_u32_e32 v105, 0x6800, v104
	ds_read2_b64 v[84:87], v105 offset1:4
	v_exp_f32_e32 v106, v80
	v_exp_f32_e32 v107, v81
	s_waitcnt lgkmcnt(0)
	v_mfma_f32_16x16x32_bf16 v[80:83], v[84:87], v[76:79], v[32:35]
	v_cvt_pk_bf16_f32 v74, v106, v107
	v_add_u32_e32 v106, 0x7800, v104
	s_nop 0
	ds_read2_b64 v[32:35], v106 offset0:32 offset1:36
	v_add_u32_e32 v107, 0x8800, v104
	s_waitcnt lgkmcnt(0)
	v_mfma_f32_16x16x32_bf16 v[40:43], v[32:35], v[76:79], v[40:43]
	v_add_u32_e32 v104, 0x9800, v104
	v_mfma_f32_16x16x32_bf16 v[60:63], v[32:35], v[72:75], v[60:63]
	ds_read2_b64 v[32:35], v107 offset0:64 offset1:68
	s_waitcnt lgkmcnt(0)
	v_mfma_f32_16x16x32_bf16 v[44:47], v[32:35], v[76:79], v[44:47]
	v_mfma_f32_16x16x32_bf16 v[64:67], v[32:35], v[72:75], v[64:67]
	ds_read2_b64 v[32:35], v104 offset0:96 offset1:100
	s_waitcnt lgkmcnt(0)
	v_mfma_f32_16x16x32_bf16 v[48:51], v[32:35], v[76:79], v[48:51]
	v_mfma_f32_16x16x32_bf16 v[52:55], v[32:35], v[72:75], v[52:55]
	v_mov_b64_e32 v[32:33], s[76:77]
	v_mov_b64_e32 v[34:35], s[78:79]
	v_readlane_b32 s77, v255, 21
	v_mfma_f32_16x16x32_bf16 v[36:39], v[84:87], v[72:75], v[36:39]
	v_exp_f32_e32 v84, v88
	v_exp_f32_e32 v85, v89
	v_exp_f32_e32 v86, v90
	v_mfma_f32_16x16x32_bf16 v[68:71], v[32:35], v[76:79], v[68:71]
	v_exp_f32_e32 v76, v100
	v_exp_f32_e32 v77, v101
	v_exp_f32_e32 v78, v102
	v_mfma_f32_16x16x32_bf16 v[56:59], v[32:35], v[72:75], v[56:59]
	v_exp_f32_e32 v72, v92
	v_exp_f32_e32 v73, v93
	v_exp_f32_e32 v74, v94
	v_exp_f32_e32 v75, v95
	v_exp_f32_e32 v79, v103
	v_cvt_pk_bf16_f32 v72, v72, v73
	v_exp_f32_e32 v87, v91
	v_cvt_pk_bf16_f32 v73, v74, v75
	v_cvt_pk_bf16_f32 v74, v76, v77
	v_cvt_pk_bf16_f32 v75, v78, v79
	ds_read2_b64 v[76:79], v105 offset0:8 offset1:12
	v_exp_f32_e32 v88, v96
	v_exp_f32_e32 v89, v97
	v_exp_f32_e32 v90, v98
	v_exp_f32_e32 v91, v99
	v_cvt_pk_bf16_f32 v84, v84, v85
	v_cvt_pk_bf16_f32 v85, v86, v87
	v_cvt_pk_bf16_f32 v86, v88, v89
	v_cvt_pk_bf16_f32 v87, v90, v91
	s_waitcnt lgkmcnt(0)
; DEV float ex2(float x) { return __builtin_amdgcn_exp2f(x); }
; DEV void attn_item(const Params& p, int bl, int head, int q0, int nkeys, char* smem, int tid) {
;     ...
;     for (int hh = 0; hh < 2; ++hh) {
;       f32x4 s[4][2];
; #pragma unroll
;       for (int kf = 0; kf < 4; ++kf) {
; #pragma unroll
;         for (int ks = 0; ks < 3; ++ks) {
;           bf16x8 a = *(const bf16x8*)(kb + (hh * 64 + kf * 16 + fr) * KROW + ks * 64 + fq * 16);
;           s[kf][0] = __builtin_amdgcn_mfma_f32_16x16x32_bf16(a, qf[0][ks], ks == 0 ? negm[0] : s[kf][0], 0, 0, 0);
;           s[kf][1] = __builtin_amdgcn_mfma_f32_16x16x32_bf16(a, qf[1][ks], ks == 0 ? negm[1] : s[kf][1], 0, 0, 0);
;         }
;       }
; #pragma unroll
;       for (int kk = 0; kk < 2; ++kk) {
;         bf16x8 pb[2];
; #pragma unroll
;         for (int qt = 0; qt < 2; ++qt) {
;           const float e0 = ex2(s[2 * kk][qt][0]), e1 = ex2(s[2 * kk][qt][1]), e2 = ex2(s[2 * kk][qt][2]), e3 = ex2(s[2 * kk][qt][3]);
;           const float e4 = ex2(s[2 * kk + 1][qt][0]), e5 = ex2(s[2 * kk + 1][qt][1]), e6 = ex2(s[2 * kk + 1][qt][2]), e7 = ex2(s[2 * kk + 1][qt][3]);
;           u32x4 cw = {pack2(e0, e1), pack2(e2, e3), pack2(e4, e5), pack2(e6, e7)};
;           pb[qt] = __builtin_bit_cast(bf16x8, cw);
;         }
;         lacc[0] = __builtin_amdgcn_mfma_f32_16x16x32_bf16(ones, pb[0], lacc[0], 0, 0, 0);
;         lacc[1] = __builtin_amdgcn_mfma_f32_16x16x32_bf16(ones, pb[1], lacc[1], 0, 0, 0);
; #pragma unroll
;         for (int dvf = 0; dvf < 4; ++dvf) {
;           const char* vp = vb + (dvf * 16 + fr) * VROW + (hh * 64 + kk * 32 + fq * 4) * 2;
;           const uint2 h0 = *(const uint2*)vp, h1 = *(const uint2*)(vp + 32);
;           u32x4 vw = {h0.x, h0.y, h1.x, h1.y};
;           const bf16x8 va = __builtin_bit_cast(bf16x8, vw);
;           o[dvf][0] = __builtin_amdgcn_mfma_f32_16x16x32_bf16(va, pb[0], o[dvf][0], 0, 0, 0);
;           o[dvf][1] = __builtin_amdgcn_mfma_f32_16x16x32_bf16(va, pb[1], o[dvf][1], 0, 0, 0);
;         }
;       }
;     }
;     if (t + 1 < nt) {
;       char* nb = smem + ((t + 1) & 1) * ASTG;
; #pragma unroll
;       for (int i = 0; i < 3; ++i) *(u32x4*)(nb + koff[i]) = kr[i];
; #pragma unroll
;       for (int i = 0; i < 2; ++i) *(u32x4*)(nb + KBYTES + voffl[i]) = vr[i];
;     }
;     __syncthreads();
	v_mfma_f32_16x16x32_bf16 v[80:83], v[76:79], v[72:75], v[80:83]
	ds_read_b128 v[92:95], v108 offset:16704
	ds_read_b128 v[100:103], v108 offset:20032
	s_mov_b32 s78, s38
	v_mfma_f32_16x16x32_bf16 v[36:39], v[76:79], v[84:87], v[36:39]
	ds_read2_b64 v[76:79], v106 offset0:40 offset1:44
	s_waitcnt lgkmcnt(0)
	v_mfma_f32_16x16x32_bf16 v[40:43], v[76:79], v[72:75], v[40:43]
	v_mfma_f32_16x16x32_bf16 v[60:63], v[76:79], v[84:87], v[60:63]
	ds_read2_b64 v[76:79], v107 offset0:72 offset1:76
	s_waitcnt lgkmcnt(0)
	v_mfma_f32_16x16x32_bf16 v[44:47], v[76:79], v[72:75], v[44:47]
	v_mfma_f32_16x16x32_bf16 v[64:67], v[76:79], v[84:87], v[64:67]
	ds_read2_b64 v[76:79], v104 offset0:104 offset1:108
	s_waitcnt lgkmcnt(0)
	v_mfma_f32_16x16x32_bf16 v[48:51], v[76:79], v[72:75], v[48:51]
	v_mfma_f32_16x16x32_bf16 v[68:71], v[32:35], v[72:75], v[68:71]
	ds_read_b128 v[72:75], v108 offset:13312
	v_mfma_f32_16x16x32_bf16 v[52:55], v[76:79], v[84:87], v[52:55]
	v_mfma_f32_16x16x32_bf16 v[56:59], v[32:35], v[84:87], v[56:59]
	ds_read_b128 v[84:87], v108 offset:13376
	s_waitcnt lgkmcnt(1)
	v_mfma_f32_16x16x32_bf16 v[76:79], v[72:75], v[12:15], v[24:27]
	v_mfma_f32_16x16x32_bf16 v[72:75], v[72:75], v[20:23], v[28:31]
	s_waitcnt lgkmcnt(0)
	v_mfma_f32_16x16x32_bf16 v[76:79], v[84:87], v[8:11], v[76:79]
	v_mfma_f32_16x16x32_bf16 v[72:75], v[84:87], v[16:19], v[72:75]
	ds_read_b128 v[84:87], v108 offset:13440
	s_waitcnt lgkmcnt(0)
	v_mfma_f32_16x16x32_bf16 v[76:79], v[84:87], v[4:7], v[76:79]
	v_mfma_f32_16x16x32_bf16 v[72:75], v[84:87], v[0:3], v[72:75]
	ds_read_b128 v[84:87], v108 offset:16640
	s_waitcnt lgkmcnt(0)
	v_mfma_f32_16x16x32_bf16 v[88:91], v[84:87], v[12:15], v[24:27]
	v_mfma_f32_16x16x32_bf16 v[84:87], v[84:87], v[20:23], v[28:31]
	v_mfma_f32_16x16x32_bf16 v[88:91], v[92:95], v[8:11], v[88:91]
	v_mfma_f32_16x16x32_bf16 v[84:87], v[92:95], v[16:19], v[84:87]
	ds_read_b128 v[92:95], v108 offset:16768
	s_waitcnt lgkmcnt(0)
	v_mfma_f32_16x16x32_bf16 v[88:91], v[92:95], v[4:7], v[88:91]
	v_mfma_f32_16x16x32_bf16 v[84:87], v[92:95], v[0:3], v[84:87]
	ds_read_b128 v[92:95], v108 offset:19968
	s_waitcnt lgkmcnt(0)
	v_mfma_f32_16x16x32_bf16 v[96:99], v[92:95], v[12:15], v[24:27]
	v_mfma_f32_16x16x32_bf16 v[92:95], v[92:95], v[20:23], v[28:31]
	v_mfma_f32_16x16x32_bf16 v[96:99], v[100:103], v[8:11], v[96:99]
	v_mfma_f32_16x16x32_bf16 v[92:95], v[100:103], v[16:19], v[92:95]
	ds_read_b128 v[100:103], v108 offset:20096
	s_waitcnt lgkmcnt(0)
	v_mfma_f32_16x16x32_bf16 v[96:99], v[100:103], v[4:7], v[96:99]
	v_mfma_f32_16x16x32_bf16 v[92:95], v[100:103], v[0:3], v[92:95]
	ds_read_b128 v[100:103], v108 offset:23296
	s_waitcnt lgkmcnt(0)
	v_mfma_f32_16x16x32_bf16 v[12:15], v[100:103], v[12:15], v[24:27]
	s_nop 2
	ds_read_b128 v[24:27], v108 offset:23360
	v_mfma_f32_16x16x32_bf16 v[20:23], v[100:103], v[20:23], v[28:31]
	s_waitcnt lgkmcnt(0)
	v_mfma_f32_16x16x32_bf16 v[8:11], v[24:27], v[8:11], v[12:15]
	v_mfma_f32_16x16x32_bf16 v[12:15], v[24:27], v[16:19], v[20:23]
	ds_read_b128 v[16:19], v108 offset:23424
	v_exp_f32_e32 v24, v84
	v_exp_f32_e32 v25, v85
	s_waitcnt lgkmcnt(0)
	v_mfma_f32_16x16x32_bf16 v[4:7], v[16:19], v[4:7], v[8:11]
	s_nop 2
	v_exp_f32_e32 v8, v76
	v_exp_f32_e32 v9, v77
	v_exp_f32_e32 v10, v78
	v_mfma_f32_16x16x32_bf16 v[0:3], v[16:19], v[0:3], v[12:15]
	v_exp_f32_e32 v11, v79
	v_cvt_pk_bf16_f32 v8, v8, v9
	v_exp_f32_e32 v16, v72
	v_exp_f32_e32 v12, v88
	v_exp_f32_e32 v13, v89
	v_exp_f32_e32 v14, v90
	v_exp_f32_e32 v15, v91
	v_cvt_pk_bf16_f32 v9, v10, v11
	v_cvt_pk_bf16_f32 v10, v12, v13
	v_exp_f32_e32 v17, v73
	v_cvt_pk_bf16_f32 v11, v14, v15
	ds_read2_b64 v[12:15], v105 offset0:16 offset1:20
	v_exp_f32_e32 v18, v74
	v_exp_f32_e32 v19, v75
	v_exp_f32_e32 v26, v86
	v_exp_f32_e32 v27, v87
	v_cvt_pk_bf16_f32 v16, v16, v17
	v_cvt_pk_bf16_f32 v17, v18, v19
	v_cvt_pk_bf16_f32 v18, v24, v25
	v_cvt_pk_bf16_f32 v19, v26, v27
	s_waitcnt lgkmcnt(0)
	v_mfma_f32_16x16x32_bf16 v[20:23], v[12:15], v[8:11], v[80:83]
	ds_read2_b64 v[24:27], v106 offset0:48 offset1:52
	v_exp_f32_e32 v0, v0
	v_exp_f32_e32 v1, v1
	v_mfma_f32_16x16x32_bf16 v[12:15], v[12:15], v[16:19], v[36:39]
	v_exp_f32_e32 v2, v2
	v_exp_f32_e32 v3, v3
	v_exp_f32_e32 v4, v4
	ds_read2_b64 v[36:39], v107 offset0:80 offset1:84
	s_waitcnt lgkmcnt(1)
	v_mfma_f32_16x16x32_bf16 v[28:31], v[24:27], v[8:11], v[40:43]
	v_exp_f32_e32 v5, v5
	v_exp_f32_e32 v6, v6
	v_exp_f32_e32 v7, v7
	s_waitcnt lgkmcnt(0)
	v_mfma_f32_16x16x32_bf16 v[40:43], v[36:39], v[8:11], v[44:47]
	v_mov_b32_e32 v84, v174
	v_mfma_f32_16x16x32_bf16 v[44:47], v[36:39], v[16:19], v[64:67]
	ds_read2_b64 v[36:39], v104 offset0:112 offset1:116
	v_mfma_f32_16x16x32_bf16 v[24:27], v[24:27], v[16:19], v[60:63]
	s_nop 0
	v_cvt_pk_bf16_f32 v66, v4, v5
	v_cvt_pk_bf16_f32 v67, v6, v7
	ds_read2_b64 v[4:7], v105 offset0:24 offset1:28
	s_waitcnt lgkmcnt(1)
	v_mfma_f32_16x16x32_bf16 v[48:51], v[36:39], v[8:11], v[48:51]
	v_mfma_f32_16x16x32_bf16 v[60:63], v[32:35], v[8:11], v[68:71]
	v_exp_f32_e32 v8, v98
	v_exp_f32_e32 v9, v99
	v_exp_f32_e32 v10, v94
	v_cvt_pk_bf16_f32 v70, v0, v1
	v_cvt_pk_bf16_f32 v71, v2, v3
	ds_read2_b64 v[0:3], v106 offset0:56 offset1:60
	v_mfma_f32_16x16x32_bf16 v[52:55], v[36:39], v[16:19], v[52:55]
	v_exp_f32_e32 v36, v96
	v_exp_f32_e32 v37, v97
	v_cvt_pk_bf16_f32 v65, v8, v9
	v_exp_f32_e32 v8, v92
	v_exp_f32_e32 v9, v93
	v_exp_f32_e32 v11, v95
	v_cvt_pk_bf16_f32 v64, v36, v37
	v_mfma_f32_16x16x32_bf16 v[56:59], v[32:35], v[16:19], v[56:59]
	v_cvt_pk_bf16_f32 v68, v8, v9
	v_cvt_pk_bf16_f32 v69, v10, v11
	s_waitcnt lgkmcnt(0)
	v_mfma_f32_16x16x32_bf16 v[28:31], v[0:3], v[64:67], v[28:31]
	v_mfma_f32_16x16x32_bf16 v[8:11], v[0:3], v[68:71], v[24:27]
	ds_read2_b64 v[0:3], v107 offset0:88 offset1:92
	v_mfma_f32_16x16x32_bf16 v[36:39], v[4:7], v[64:67], v[20:23]
	s_nop 0
	v_or_b32_e32 v24, s8, v175
	v_mfma_f32_16x16x32_bf16 v[12:15], v[4:7], v[68:71], v[12:15]
	s_waitcnt lgkmcnt(0)
	v_mfma_f32_16x16x32_bf16 v[20:23], v[0:3], v[64:67], v[40:43]
	v_mfma_f32_16x16x32_bf16 v[4:7], v[0:3], v[68:71], v[44:47]
	ds_read2_b64 v[0:3], v104 offset0:120 offset1:124
	s_waitcnt lgkmcnt(0)
	s_barrier
	v_mfma_f32_16x16x32_bf16 v[16:19], v[0:3], v[64:67], v[48:51]
	v_add_u32_e32 v44, v24, v158
	v_mfma_f32_16x16x32_bf16 v[0:3], v[0:3], v[68:71], v[52:55]
	v_mfma_f32_16x16x32_bf16 v[40:43], v[32:35], v[64:67], v[60:63]
	v_mfma_f32_16x16x32_bf16 v[24:27], v[32:35], v[68:71], v[56:59]
	s_branch .LBB0_985

; #define OPQ int tid = tid0; asm volatile("" : "+v"(tid));
; DEV void conv_item(const Params& p, int l, int item, int tid) {
;   const int tok0 = item * 16;
;   const int bl = tok0 / NTOK, jt = tok0 % NTOK;
;   const int lo = jt < NCTX ? 0 : NCTX, hi = jt < NCTX ? NCTX : NTOK;
;   const int ch0 = (tid & 63) * 8, tr = tid >> 6;
;   const int jb = jt + tr * 2;
;   const u16* zb = p.z + (long)bl * NTOK * NINP;
;   uint4 xa[4], xc[4], bq[2], gq[2];
; #pragma unroll
;   for (int i = 0; i < 4; ++i) {
;     const int j = jb - 1 + i;
;     const bool ok = j >= lo && j < hi;
;     const int jc = ok ? j : jb;
;     xa[i] = *(const uint4*)(zb + (long)jc * NINP + C_CX + ch0);
;     xc[i] = *(const uint4*)(zb + (long)jc * NINP + C_CC + ch0);
;     if (!ok) xa[i] = make_uint4(0u, 0u, 0u, 0u);
;   }
; #pragma unroll
;   for (int i = 0; i < 2; ++i) {
;     bq[i] = *(const uint4*)(zb + (long)(jb + i) * NINP + C_CB + ch0);
;     gq[i] = *(const uint4*)(zb + (long)(jb + i) * NINP + C_GCV + ch0);
;   }
; __global__ void __launch_bounds__(512) mega(Params p, int coop) {
;     ...
;         for (int it = bid; it < (last ? G * (SEQ / 16) : TG / 16); it += nb) {
;           OPQ
;           conv_item(p, l, last ? (it >> 7) * (NTOK / 16) + (NCTX / 16) + (it & 127) : it, tid);
.LBB0_1120:
	v_readlane_b32 s44, v255, 42
	v_readlane_b32 s45, v255, 43
	s_and_b64 s[6:7], s[44:45], exec
	s_movk_i32 s6, 0x480
	s_cselect_b32 s6, 0x400, s6
	v_readlane_b32 s75, v253, 6
	v_readlane_b32 s40, v255, 17
	s_cmp_ge_i32 s75, s6
	v_readlane_b32 s62, v253, 2
	v_readlane_b32 s22, v255, 26
	s_movk_i32 s72, 0x100
	s_mov_b32 s73, 0x1a000
	v_readlane_b32 s42, v255, 19
	v_readlane_b32 s43, v255, 20
	v_readlane_b32 s63, v253, 3
	v_readlane_b32 s41, v255, 18
	s_cbranch_scc1 .LBB0_1125
	s_mul_i32 s7, s14, 0x600
	s_mov_b32 s64, s62
	s_add_i32 s8, s7, 0x400
	s_mov_b32 s9, s75
	v_and_b32_e32 v0, 63, v197
	v_lshrrev_b32_e32 v1, 6, v197
	v_lshlrev_b32_e32 v122, 4, v0
	v_lshlrev_b32_e32 v123, 5, v0
	v_readfirstlane_b32 s48, v1
	v_add_u32_e32 v118, 0x1b40, v122
	v_add_u32_e32 v119, 0x2340, v122
	v_add_u32_e32 v120, 0x1f40, v122
	v_add_u32_e32 v121, 0x2740, v122
	v_readlane_b32 s12, v253, 0
	v_readlane_b32 s13, v253, 1
	s_lshl_b32 s48, s48, 1
	s_load_dwordx2 s[54:55], s[12:13], 0x78
	s_lshl_b32 s10, s7, 2
	s_add_u32 s50, s42, s10
	s_addc_u32 s51, s43, 0
	s_add_u32 s52, s50, 0x1000
	s_addc_u32 s53, s51, 0
	global_load_dwordx4 v[124:127], v123, s[50:51]
	global_load_dwordx4 v[128:131], v123, s[50:51] offset:16
	global_load_dwordx4 v[132:135], v123, s[50:51] offset:2048
	global_load_dwordx4 v[136:139], v123, s[50:51] offset:2064
	global_load_dwordx4 v[140:143], v123, s[52:53]
	global_load_dwordx4 v[144:147], v123, s[52:53] offset:16
	s_lshl_b32 s10, s14, 11
	s_waitcnt lgkmcnt(0)
	s_add_u32 s54, s54, s10
	s_addc_u32 s55, s55, 0
	global_load_dwordx4 v[148:151], v123, s[54:55]
	global_load_dwordx4 v[152:155], v123, s[54:55] offset:16
.Lcv_loop:
	s_mov_b32 s10, s9
	s_and_b64 s[12:13], s[44:45], exec
	s_cbranch_scc0 .Lcv_nomap
	s_ashr_i32 s10, s9, 7
	s_mulk_i32 s10, 0x90
	s_and_b32 s11, s9, 0x7f
	s_add_i32 s10, s11, s10
	s_add_i32 s10, s10, 16
.Lcv_nomap:
	s_lshl_b32 s11, s10, 4
	s_mul_hi_u32 s12, s10, 0x38e38e39
	s_lshr_b32 s12, s12, 5
	s_mul_i32 s13, s12, 0x900
	s_sub_i32 s11, s11, s13
	s_cmpk_lt_i32 s11, 0x100
	s_cselect_b32 s15, 0, 0x100
	s_cselect_b32 s23, s72, 0x900
	s_add_i32 s11, s11, s48
	s_add_i32 s24, s13, s11
	s_add_i32 s24, s24, 0x9000
	s_lshl_b32 s24, s24, 10
	v_readlane_b32 s60, v254, 62
	v_readlane_b32 s61, v254, 63
	s_mul_i32 s12, s12, 0x2640000
	s_mul_i32 s13, s11, 0x4400
	s_add_u32 s58, s60, s24
	s_addc_u32 s59, s61, 0
	s_add_u32 s12, s12, s13
	s_add_u32 s52, s88, s12
	s_addc_u32 s53, s89, 0
	s_add_u32 s54, s52, 0x4400
	s_addc_u32 s55, s53, 0
	s_cmp_gt_i32 s11, s15
	s_cselect_b32 s60, 1, 0
	s_cselect_b32 s32, 0x4400, 0
	s_sub_u32 s50, s52, s32
	s_subb_u32 s51, s53, 0
	s_add_i32 s13, s11, 2
	s_cmp_lt_i32 s13, s23
	s_cselect_b32 s61, 1, 0
	s_cselect_b32 s32, 0x8800, 0
	s_add_u32 s56, s52, s32
	s_addc_u32 s57, s53, 0
	global_load_dwordx4 v[158:161], v118, s[50:51]
	global_load_dwordx4 v[174:177], v119, s[50:51]
	global_load_dwordx4 v[162:165], v118, s[52:53]
	global_load_dwordx4 v[178:181], v119, s[52:53]
	global_load_dwordx4 v[166:169], v118, s[54:55]
	global_load_dwordx4 v[182:185], v119, s[54:55]
	global_load_dwordx4 v[170:173], v118, s[56:57]
	global_load_dwordx4 v[186:189], v119, s[56:57]
	global_load_dwordx4 v[198:201], v120, s[52:53]
	global_load_dwordx4 v[206:209], v121, s[52:53]
	global_load_dwordx4 v[202:205], v120, s[54:55]
	global_load_dwordx4 v[210:213], v121, s[54:55]
	s_waitcnt vmcnt(0)
	s_cmp_lg_u32 s60, 0
	s_cbranch_scc1 .Lcv_ok0
	v_mov_b32_e32 v158, 0
	v_mov_b32_e32 v159, 0
	v_mov_b32_e32 v160, 0
	v_mov_b32_e32 v161, 0
.Lcv_ok0:
	s_cmp_lg_u32 s61, 0
	s_cbranch_scc1 .Lcv_ok3
	v_mov_b32_e32 v170, 0
	v_mov_b32_e32 v171, 0
	v_mov_b32_e32 v172, 0
	v_mov_b32_e32 v173, 0
; DEV float bflo(unsigned w) { return __uint_as_float(w << 16); }
; DEV float bfhi(unsigned w) { return __uint_as_float(w & 0xffff0000u); }
; DEV void conv_item(const Params& p, int l, int item, int tid) {
;     ...
;   float u[4][8];
; #pragma unroll
;   for (int i = 0; i < 4; ++i) {
;     u[i][0] = bflo(xa[i].x) * bflo(xc[i].x); u[i][1] = bfhi(xa[i].x) * bfhi(xc[i].x);
;     u[i][2] = bflo(xa[i].y) * bflo(xc[i].y); u[i][3] = bfhi(xa[i].y) * bfhi(xc[i].y);
;     u[i][4] = bflo(xa[i].z) * bflo(xc[i].z); u[i][5] = bfhi(xa[i].z) * bfhi(xc[i].z);
;     u[i][6] = bflo(xa[i].w) * bflo(xc[i].w); u[i][7] = bfhi(xa[i].w) * bfhi(xc[i].w);
;   }
; #pragma unroll
;   for (int i = 0; i < 2; ++i) {
;     const uint4 b = bq[i], gg = gq[i];
;     const float bv[8] = {bflo(b.x), bfhi(b.x), bflo(b.y), bfhi(b.y), bflo(b.z), bfhi(b.z), bflo(b.w), bfhi(b.w)};
;     const float gv[8] = {bflo(gg.x), bfhi(gg.x), bflo(gg.y), bfhi(gg.y), bflo(gg.z), bfhi(gg.z), bflo(gg.w), bfhi(gg.w)};
;     float y[8];
; #pragma unroll
;     for (int k = 0; k < 8; ++k) y[k] = bv[k] * (u[i][k] * w0[k] + u[i + 1][k] * w1[k] + u[i + 2][k] * w2[k] + bb[k]) * gv[k];
;     uint4 ov;
;     ov.x = pack2(y[0], y[1]); ov.y = pack2(y[2], y[3]); ov.z = pack2(y[4], y[5]); ov.w = pack2(y[6], y[7]);
;     *(uint4*)(p.Y + ((long)2 * TG + (long)bl * NTOK + jb + i) * 512 + ch0) = ov;
;   }
.Lcv_ok3:
	v_lshlrev_b32_e32 v0, 16, v158
	v_and_b32_e32 v1, 0xffff0000, v158
	v_lshlrev_b32_e32 v2, 16, v174
	v_and_b32_e32 v3, 0xffff0000, v174
	v_lshlrev_b32_e32 v4, 16, v159
	v_and_b32_e32 v5, 0xffff0000, v159
	v_lshlrev_b32_e32 v6, 16, v175
	v_and_b32_e32 v7, 0xffff0000, v175
	v_lshlrev_b32_e32 v8, 16, v160
	v_and_b32_e32 v9, 0xffff0000, v160
	v_lshlrev_b32_e32 v10, 16, v176
	v_and_b32_e32 v11, 0xffff0000, v176
	v_lshlrev_b32_e32 v12, 16, v161
	v_and_b32_e32 v13, 0xffff0000, v161
	v_lshlrev_b32_e32 v14, 16, v177
	v_and_b32_e32 v15, 0xffff0000, v177
	v_pk_mul_f32 v[214:215], v[2:3], v[0:1]
	v_pk_mul_f32 v[216:217], v[6:7], v[4:5]
	v_pk_mul_f32 v[218:219], v[10:11], v[8:9]
	v_pk_mul_f32 v[220:221], v[14:15], v[12:13]
	v_lshlrev_b32_e32 v0, 16, v162
	v_and_b32_e32 v1, 0xffff0000, v162
	v_lshlrev_b32_e32 v2, 16, v178
	v_and_b32_e32 v3, 0xffff0000, v178
	v_lshlrev_b32_e32 v4, 16, v163
	v_and_b32_e32 v5, 0xffff0000, v163
	v_lshlrev_b32_e32 v6, 16, v179
	v_and_b32_e32 v7, 0xffff0000, v179
	v_lshlrev_b32_e32 v8, 16, v164
	v_and_b32_e32 v9, 0xffff0000, v164
	v_lshlrev_b32_e32 v10, 16, v180
	v_and_b32_e32 v11, 0xffff0000, v180
	v_lshlrev_b32_e32 v12, 16, v165
	v_and_b32_e32 v13, 0xffff0000, v165
	v_lshlrev_b32_e32 v14, 16, v181
	v_and_b32_e32 v15, 0xffff0000, v181
	v_pk_mul_f32 v[222:223], v[2:3], v[0:1]
	v_pk_mul_f32 v[224:225], v[6:7], v[4:5]
	v_pk_mul_f32 v[226:227], v[10:11], v[8:9]
	v_pk_mul_f32 v[228:229], v[14:15], v[12:13]
	v_lshlrev_b32_e32 v0, 16, v166
	v_and_b32_e32 v1, 0xffff0000, v166
	v_lshlrev_b32_e32 v2, 16, v182
	v_and_b32_e32 v3, 0xffff0000, v182
	v_lshlrev_b32_e32 v4, 16, v167
	v_and_b32_e32 v5, 0xffff0000, v167
	v_lshlrev_b32_e32 v6, 16, v183
	v_and_b32_e32 v7, 0xffff0000, v183
	v_lshlrev_b32_e32 v8, 16, v168
	v_and_b32_e32 v9, 0xffff0000, v168
	v_lshlrev_b32_e32 v10, 16, v184
	v_and_b32_e32 v11, 0xffff0000, v184
	v_lshlrev_b32_e32 v12, 16, v169
	v_and_b32_e32 v13, 0xffff0000, v169
	v_lshlrev_b32_e32 v14, 16, v185
	v_and_b32_e32 v15, 0xffff0000, v185
	v_pk_mul_f32 v[230:231], v[2:3], v[0:1]
	v_pk_mul_f32 v[232:233], v[6:7], v[4:5]
	v_pk_mul_f32 v[234:235], v[10:11], v[8:9]
	v_pk_mul_f32 v[236:237], v[14:15], v[12:13]
	v_lshlrev_b32_e32 v0, 16, v170
	v_and_b32_e32 v1, 0xffff0000, v170
	v_lshlrev_b32_e32 v2, 16, v186
	v_and_b32_e32 v3, 0xffff0000, v186
	v_lshlrev_b32_e32 v4, 16, v171
	v_and_b32_e32 v5, 0xffff0000, v171
	v_lshlrev_b32_e32 v6, 16, v187
	v_and_b32_e32 v7, 0xffff0000, v187
	v_lshlrev_b32_e32 v8, 16, v172
	v_and_b32_e32 v9, 0xffff0000, v172
	v_lshlrev_b32_e32 v10, 16, v188
	v_and_b32_e32 v11, 0xffff0000, v188
	v_lshlrev_b32_e32 v12, 16, v173
	v_and_b32_e32 v13, 0xffff0000, v173
	v_lshlrev_b32_e32 v14, 16, v189
	v_and_b32_e32 v15, 0xffff0000, v189
	v_pk_mul_f32 v[238:239], v[2:3], v[0:1]
	v_pk_mul_f32 v[240:241], v[6:7], v[4:5]
	v_pk_mul_f32 v[242:243], v[10:11], v[8:9]
	v_pk_mul_f32 v[244:245], v[14:15], v[12:13]
	v_pk_mul_f32 v[16:17], v[222:223], v[132:133]
	v_pk_mul_f32 v[18:19], v[224:225], v[134:135]
	v_pk_mul_f32 v[20:21], v[226:227], v[136:137]
	v_pk_mul_f32 v[22:23], v[228:229], v[138:139]
	v_pk_fma_f32 v[16:17], v[214:215], v[124:125], v[16:17]
	v_pk_fma_f32 v[18:19], v[216:217], v[126:127], v[18:19]
	v_pk_fma_f32 v[20:21], v[218:219], v[128:129], v[20:21]
	v_pk_fma_f32 v[22:23], v[220:221], v[130:131], v[22:23]
	v_pk_fma_f32 v[16:17], v[230:231], v[140:141], v[16:17]
	v_pk_fma_f32 v[18:19], v[232:233], v[142:143], v[18:19]
	v_pk_fma_f32 v[20:21], v[234:235], v[144:145], v[20:21]
	v_pk_fma_f32 v[22:23], v[236:237], v[146:147], v[22:23]
	v_pk_add_f32 v[16:17], v[148:149], v[16:17]
	v_pk_add_f32 v[18:19], v[150:151], v[18:19]
	v_pk_add_f32 v[20:21], v[152:153], v[20:21]
	v_pk_add_f32 v[22:23], v[154:155], v[22:23]
	v_lshlrev_b32_e32 v24, 16, v198
	v_and_b32_e32 v25, 0xffff0000, v198
	v_lshlrev_b32_e32 v26, 16, v199
	v_and_b32_e32 v27, 0xffff0000, v199
	v_lshlrev_b32_e32 v28, 16, v200
	v_and_b32_e32 v29, 0xffff0000, v200
	v_lshlrev_b32_e32 v30, 16, v201
	v_and_b32_e32 v31, 0xffff0000, v201
	v_pk_mul_f32 v[16:17], v[16:17], v[24:25]
	v_pk_mul_f32 v[18:19], v[18:19], v[26:27]
	v_pk_mul_f32 v[20:21], v[20:21], v[28:29]
	v_pk_mul_f32 v[22:23], v[22:23], v[30:31]
	v_lshlrev_b32_e32 v24, 16, v206
	v_and_b32_e32 v25, 0xffff0000, v206
	v_lshlrev_b32_e32 v26, 16, v207
	v_and_b32_e32 v27, 0xffff0000, v207
	v_lshlrev_b32_e32 v28, 16, v208
	v_and_b32_e32 v29, 0xffff0000, v208
	v_lshlrev_b32_e32 v30, 16, v209
	v_and_b32_e32 v31, 0xffff0000, v209
	v_pk_mul_f32 v[16:17], v[16:17], v[24:25]
	v_pk_mul_f32 v[18:19], v[18:19], v[26:27]
	v_pk_mul_f32 v[20:21], v[20:21], v[28:29]
	v_pk_mul_f32 v[22:23], v[22:23], v[30:31]
	v_cvt_pk_bf16_f32 v64, v16, v17
	v_cvt_pk_bf16_f32 v65, v18, v19
	v_cvt_pk_bf16_f32 v66, v20, v21
	v_cvt_pk_bf16_f32 v67, v22, v23
	global_store_dwordx4 v122, v[64:67], s[58:59]
	v_pk_mul_f32 v[16:17], v[230:231], v[132:133]
	v_pk_mul_f32 v[18:19], v[232:233], v[134:135]
	v_pk_mul_f32 v[20:21], v[234:235], v[136:137]
	v_pk_mul_f32 v[22:23], v[236:237], v[138:139]
	v_pk_fma_f32 v[16:17], v[222:223], v[124:125], v[16:17]
	v_pk_fma_f32 v[18:19], v[224:225], v[126:127], v[18:19]
	v_pk_fma_f32 v[20:21], v[226:227], v[128:129], v[20:21]
	v_pk_fma_f32 v[22:23], v[228:229], v[130:131], v[22:23]
	v_pk_fma_f32 v[16:17], v[238:239], v[140:141], v[16:17]
	v_pk_fma_f32 v[18:19], v[240:241], v[142:143], v[18:19]
	v_pk_fma_f32 v[20:21], v[242:243], v[144:145], v[20:21]
	v_pk_fma_f32 v[22:23], v[244:245], v[146:147], v[22:23]
	v_pk_add_f32 v[16:17], v[148:149], v[16:17]
	v_pk_add_f32 v[18:19], v[150:151], v[18:19]
	v_pk_add_f32 v[20:21], v[152:153], v[20:21]
	v_pk_add_f32 v[22:23], v[154:155], v[22:23]
	v_lshlrev_b32_e32 v24, 16, v202
	v_and_b32_e32 v25, 0xffff0000, v202
	v_lshlrev_b32_e32 v26, 16, v203
	v_and_b32_e32 v27, 0xffff0000, v203
	v_lshlrev_b32_e32 v28, 16, v204
	v_and_b32_e32 v29, 0xffff0000, v204
	v_lshlrev_b32_e32 v30, 16, v205
	v_and_b32_e32 v31, 0xffff0000, v205
	v_pk_mul_f32 v[16:17], v[16:17], v[24:25]
	v_pk_mul_f32 v[18:19], v[18:19], v[26:27]
	v_pk_mul_f32 v[20:21], v[20:21], v[28:29]
	v_pk_mul_f32 v[22:23], v[22:23], v[30:31]
	v_lshlrev_b32_e32 v24, 16, v210
	v_and_b32_e32 v25, 0xffff0000, v210
	v_lshlrev_b32_e32 v26, 16, v211
	v_and_b32_e32 v27, 0xffff0000, v211
	v_lshlrev_b32_e32 v28, 16, v212
	v_and_b32_e32 v29, 0xffff0000, v212
	v_lshlrev_b32_e32 v30, 16, v213
	v_and_b32_e32 v31, 0xffff0000, v213
	v_pk_mul_f32 v[16:17], v[16:17], v[24:25]
	v_pk_mul_f32 v[18:19], v[18:19], v[26:27]
	v_pk_mul_f32 v[20:21], v[20:21], v[28:29]
	v_pk_mul_f32 v[22:23], v[22:23], v[30:31]
	v_cvt_pk_bf16_f32 v68, v16, v17
	v_cvt_pk_bf16_f32 v69, v18, v19
	v_cvt_pk_bf16_f32 v70, v20, v21
	v_cvt_pk_bf16_f32 v71, v22, v23
	global_store_dwordx4 v122, v[68:71], s[58:59] offset:1024
	s_add_i32 s9, s9, s64
	s_cmp_ge_i32 s9, s6
	s_cbranch_scc0 .Lcv_loop
	v_readlane_b32 s16, v254, 62
	v_readlane_b32 s17, v254, 63
	v_readlane_b32 s18, v255, 0
	v_readlane_b32 s19, v255, 1

; #define OPQ int tid = tid0; asm volatile("" : "+v"(tid));
; DEV void final_norm_item(const Params& p, int g, int item, int tid) {
;   const int wid = tid >> 6, lane = tid & 63;
;   const int r = item * 8 + wid;
;   float* row = p.out + ((long)g * G * SEQ + r) * D;
;   float4 v[4];
;   float ss = 0.f;
; #pragma unroll
;   for (int i = 0; i < 4; ++i) {
;     v[i] = *(const float4*)(row + i * 256 + lane * 4);
;     ss += v[i].x * v[i].x + v[i].y * v[i].y + v[i].z * v[i].z + v[i].w * v[i].w;
;   }
;   ss = wsum(ss, lane);
;   const float rstd = rsqrtf(ss * (1.f / D) + 1e-6f);
; #pragma unroll
;   for (int i = 0; i < 4; ++i) {
;     int col = i * 256 + lane * 4;
;     float4 gg = *(const float4*)(p.final_g + col);
;     float4 o = make_float4(v[i].x * rstd * gg.x, v[i].y * rstd * gg.y, v[i].z * rstd * gg.z, v[i].w * rstd * gg.w);
;     *(float4*)(row + col) = o;
;   }
; }
; __global__ void __launch_bounds__(512) mega(Params p, int coop) {
;     ...
;     for (int it = bid; it < G * SEQ / 8; it += nb) { OPQ final_norm_item(p, g, it, tid); }
.LBB0_1332:
	v_readlane_b32 s6, v254, 30
	v_readlane_b32 s7, v254, 31
	v_readlane_b32 s40, v253, 7
	s_andn2_b64 vcc, exec, s[6:7]
	v_readlane_b32 s41, v253, 8
	v_readlane_b32 s42, v253, 9
	v_readlane_b32 s43, v253, 10
	s_movk_i32 s10, 0x80
	s_mov_b32 s11, 0x800000
	v_readlane_b32 s12, v255, 28
	v_readlane_b32 s14, v253, 2
	v_readlane_b32 s44, v253, 11
	v_readlane_b32 s45, v253, 12
	v_readlane_b32 s46, v253, 13
	v_readlane_b32 s47, v253, 14
	v_readlane_b32 s48, v253, 15
	v_readlane_b32 s49, v253, 16
	v_readlane_b32 s50, v253, 17
	v_readlane_b32 s51, v253, 18
	v_readlane_b32 s52, v253, 19
	v_readlane_b32 s53, v253, 20
	v_readlane_b32 s54, v253, 21
	v_readlane_b32 s55, v253, 22
	v_readlane_b32 s15, v253, 3
	s_cbranch_vccnz .LBB0_100
	s_lshl_b32 s6, s12, 26
	s_add_u32 s6, s42, s6
	s_addc_u32 s7, s43, 0
	s_cmp_eq_u32 s14, 0x100
	s_cbranch_scc0 .Lfn_generic
	v_readlane_b32 s8, v254, 36
	v_and_b32_e32 v32, 63, v197
	v_lshrrev_b32_e32 v33, 6, v197
	v_lshlrev_b32_e32 v156, 4, v32
	v_lshlrev_b32_e32 v34, 2, v197
	v_readfirstlane_b32 s60, v33
	v_xor_b32_e32 v64, 0x80, v34
	v_and_b32_e32 v64, 0xfc, v64
	v_xor_b32_e32 v65, 0x40, v34
	v_and_b32_e32 v65, 0xfc, v65
	v_xor_b32_e32 v66, 0x20, v34
	v_and_b32_e32 v66, 0xfc, v66
	v_xor_b32_e32 v67, 0x10, v34
	v_and_b32_e32 v67, 0xfc, v67
	v_xor_b32_e32 v68, 0x8, v34
	v_and_b32_e32 v68, 0xfc, v68
	v_xor_b32_e32 v69, 0x4, v34
	v_and_b32_e32 v69, 0xfc, v69
	global_load_dwordx4 v[96:99], v156, s[40:41]
	global_load_dwordx4 v[100:103], v156, s[40:41] offset:1024
	global_load_dwordx4 v[104:107], v156, s[40:41] offset:2048
	global_load_dwordx4 v[108:111], v156, s[40:41] offset:3072
	s_add_i32 s13, s8, s60
	s_lshl_b32 s13, s13, 12
	s_add_u32 s62, s6, s13
	s_addc_u32 s63, s7, 0
	s_add_i32 s8, s8, s24
	global_load_dwordx4 v[0:3], v156, s[62:63]
	global_load_dwordx4 v[4:7], v156, s[62:63] offset:1024
	global_load_dwordx4 v[8:11], v156, s[62:63] offset:2048
	global_load_dwordx4 v[12:15], v156, s[62:63] offset:3072
	s_add_i32 s13, s8, s60
	s_lshl_b32 s13, s13, 12
	s_add_u32 s56, s6, s13
	s_addc_u32 s57, s7, 0
	s_add_i32 s8, s8, s24
	global_load_dwordx4 v[16:19], v156, s[56:57]
	global_load_dwordx4 v[20:23], v156, s[56:57] offset:1024
	global_load_dwordx4 v[24:27], v156, s[56:57] offset:2048
	global_load_dwordx4 v[28:31], v156, s[56:57] offset:3072
	s_waitcnt vmcnt(4)
	v_mov_b32_e32 v116, v1
	v_mov_b32_e32 v117, v5
	v_mov_b32_e32 v114, v0
	v_mov_b32_e32 v115, v4
	v_mov_b32_e32 v124, v9
	v_mov_b32_e32 v125, v13
	v_pk_mul_f32 v[116:117], v[116:117], v[116:117]
	v_mov_b32_e32 v32, v2
	v_mov_b32_e32 v33, v6
	v_mov_b32_e32 v122, v8
	v_mov_b32_e32 v123, v12
	v_pk_mul_f32 v[124:125], v[124:125], v[124:125]
	v_pk_fma_f32 v[114:115], v[114:115], v[114:115], v[116:117]
	v_mov_b32_e32 v112, v3
	v_mov_b32_e32 v113, v7
	v_mov_b32_e32 v118, v10
	v_mov_b32_e32 v119, v14
	v_pk_fma_f32 v[116:117], v[122:123], v[122:123], v[124:125]
	v_pk_fma_f32 v[32:33], v[32:33], v[32:33], v[114:115]
	v_mov_b32_e32 v120, v11
	v_mov_b32_e32 v121, v15
	v_pk_fma_f32 v[114:115], v[118:119], v[118:119], v[116:117]
	v_pk_fma_f32 v[32:33], v[112:113], v[112:113], v[32:33]
	v_pk_fma_f32 v[112:113], v[120:121], v[120:121], v[114:115]
	v_add_f32_e32 v32, v32, v33
	v_add_f32_e32 v32, v32, v112
	v_add_f32_e32 v32, v32, v113
	ds_bpermute_b32 v33, v64, v32
	s_waitcnt lgkmcnt(0)
	v_add_f32_e32 v32, v32, v33
	ds_bpermute_b32 v33, v65, v32
	s_waitcnt lgkmcnt(0)
	v_add_f32_e32 v32, v32, v33
	ds_bpermute_b32 v33, v66, v32
	s_waitcnt lgkmcnt(0)
	v_add_f32_e32 v32, v32, v33
	ds_bpermute_b32 v33, v67, v32
	s_waitcnt lgkmcnt(0)
	v_add_f32_e32 v32, v32, v33
	ds_bpermute_b32 v33, v68, v32
	s_waitcnt lgkmcnt(0)
	v_add_f32_e32 v32, v32, v33
	ds_bpermute_b32 v33, v69, v32
	s_waitcnt lgkmcnt(0)
	v_add_f32_e32 v32, v32, v33
	v_fmamk_f32 v32, v32, 0x3a800000, v196
	v_cmp_gt_f32_e32 vcc, s11, v32
	v_mul_f32_e32 v33, 0x4b800000, v32
	s_nop 1
	v_cndmask_b32_e32 v32, v32, v33, vcc
	v_rsq_f32_e32 v34, v32
	s_nop 0
	v_mul_f32_e32 v33, 0x45800000, v34
	v_cndmask_b32_e32 v34, v34, v33, vcc
	v_pk_mul_f32 v[126:127], v[0:1], v[34:35] op_sel_hi:[1,0]
	v_pk_mul_f32 v[128:129], v[2:3], v[34:35] op_sel_hi:[1,0]
	v_pk_mul_f32 v[126:127], v[96:97], v[126:127]
	v_pk_mul_f32 v[128:129], v[98:99], v[128:129]
	global_store_dwordx4 v156, v[126:129], s[62:63]
	v_pk_mul_f32 v[130:131], v[4:5], v[34:35] op_sel_hi:[1,0]
	v_pk_mul_f32 v[132:133], v[6:7], v[34:35] op_sel_hi:[1,0]
	v_pk_mul_f32 v[130:131], v[100:101], v[130:131]
	v_pk_mul_f32 v[132:133], v[102:103], v[132:133]
	global_store_dwordx4 v156, v[130:133], s[62:63] offset:1024
	v_pk_mul_f32 v[134:135], v[8:9], v[34:35] op_sel_hi:[1,0]
	v_pk_mul_f32 v[136:137], v[10:11], v[34:35] op_sel_hi:[1,0]
	v_pk_mul_f32 v[134:135], v[104:105], v[134:135]
	v_pk_mul_f32 v[136:137], v[106:107], v[136:137]
	global_store_dwordx4 v156, v[134:137], s[62:63] offset:2048
	v_pk_mul_f32 v[138:139], v[12:13], v[34:35] op_sel_hi:[1,0]
	v_pk_mul_f32 v[140:141], v[14:15], v[34:35] op_sel_hi:[1,0]
	v_pk_mul_f32 v[138:139], v[108:109], v[138:139]
	v_pk_mul_f32 v[140:141], v[110:111], v[140:141]
	global_store_dwordx4 v156, v[138:141], s[62:63] offset:3072
	s_mov_b32 s15, 3
; DEV void final_norm_item(const Params& p, int g, int item, int tid) {
;   const int wid = tid >> 6, lane = tid & 63;
;   const int r = item * 8 + wid;
;   float* row = p.out + ((long)g * G * SEQ + r) * D;
;   float4 v[4];
;   float ss = 0.f;
; #pragma unroll
;   for (int i = 0; i < 4; ++i) {
;     v[i] = *(const float4*)(row + i * 256 + lane * 4);
;     ss += v[i].x * v[i].x + v[i].y * v[i].y + v[i].z * v[i].z + v[i].w * v[i].w;
;   }
;   ss = wsum(ss, lane);
;   const float rstd = rsqrtf(ss * (1.f / D) + 1e-6f);
; #pragma unroll
;   for (int i = 0; i < 4; ++i) {
;     int col = i * 256 + lane * 4;
;     float4 gg = *(const float4*)(p.final_g + col);
;     float4 o = make_float4(v[i].x * rstd * gg.x, v[i].y * rstd * gg.y, v[i].z * rstd * gg.z, v[i].w * rstd * gg.w);
;     *(float4*)(row + col) = o;
;   }
; }
.Lfn_loop:
	s_add_i32 s13, s8, s60
	s_lshl_b32 s13, s13, 12
	s_add_u32 s62, s6, s13
	s_addc_u32 s63, s7, 0
	s_add_i32 s8, s8, s24
	global_load_dwordx4 v[0:3], v156, s[62:63]
	global_load_dwordx4 v[4:7], v156, s[62:63] offset:1024
	global_load_dwordx4 v[8:11], v156, s[62:63] offset:2048
	global_load_dwordx4 v[12:15], v156, s[62:63] offset:3072
	s_waitcnt vmcnt(8)
	v_mov_b32_e32 v116, v17
	v_mov_b32_e32 v117, v21
	v_mov_b32_e32 v114, v16
	v_mov_b32_e32 v115, v20
	v_mov_b32_e32 v124, v25
	v_mov_b32_e32 v125, v29
	v_pk_mul_f32 v[116:117], v[116:117], v[116:117]
	v_mov_b32_e32 v32, v18
	v_mov_b32_e32 v33, v22
	v_mov_b32_e32 v122, v24
	v_mov_b32_e32 v123, v28
	v_pk_mul_f32 v[124:125], v[124:125], v[124:125]
	v_pk_fma_f32 v[114:115], v[114:115], v[114:115], v[116:117]
	v_mov_b32_e32 v112, v19
	v_mov_b32_e32 v113, v23
	v_mov_b32_e32 v118, v26
	v_mov_b32_e32 v119, v30
	v_pk_fma_f32 v[116:117], v[122:123], v[122:123], v[124:125]
	v_pk_fma_f32 v[32:33], v[32:33], v[32:33], v[114:115]
	v_mov_b32_e32 v120, v27
	v_mov_b32_e32 v121, v31
	v_pk_fma_f32 v[114:115], v[118:119], v[118:119], v[116:117]
	v_pk_fma_f32 v[32:33], v[112:113], v[112:113], v[32:33]
	v_pk_fma_f32 v[112:113], v[120:121], v[120:121], v[114:115]
	v_add_f32_e32 v32, v32, v33
	v_add_f32_e32 v32, v32, v112
	v_add_f32_e32 v32, v32, v113
	ds_bpermute_b32 v33, v64, v32
	s_waitcnt lgkmcnt(0)
	v_add_f32_e32 v32, v32, v33
	ds_bpermute_b32 v33, v65, v32
	s_waitcnt lgkmcnt(0)
	v_add_f32_e32 v32, v32, v33
	ds_bpermute_b32 v33, v66, v32
	s_waitcnt lgkmcnt(0)
	v_add_f32_e32 v32, v32, v33
	ds_bpermute_b32 v33, v67, v32
	s_waitcnt lgkmcnt(0)
	v_add_f32_e32 v32, v32, v33
	ds_bpermute_b32 v33, v68, v32
	s_waitcnt lgkmcnt(0)
	v_add_f32_e32 v32, v32, v33
	ds_bpermute_b32 v33, v69, v32
	s_waitcnt lgkmcnt(0)
	v_add_f32_e32 v32, v32, v33
	v_fmamk_f32 v32, v32, 0x3a800000, v196
	v_cmp_gt_f32_e32 vcc, s11, v32
	v_mul_f32_e32 v33, 0x4b800000, v32
	s_nop 1
	v_cndmask_b32_e32 v32, v32, v33, vcc
	v_rsq_f32_e32 v34, v32
	s_nop 0
	v_mul_f32_e32 v33, 0x45800000, v34
	v_cndmask_b32_e32 v34, v34, v33, vcc
	v_pk_mul_f32 v[126:127], v[16:17], v[34:35] op_sel_hi:[1,0]
	v_pk_mul_f32 v[128:129], v[18:19], v[34:35] op_sel_hi:[1,0]
	v_pk_mul_f32 v[126:127], v[96:97], v[126:127]
	v_pk_mul_f32 v[128:129], v[98:99], v[128:129]
	global_store_dwordx4 v156, v[126:129], s[56:57]
	v_pk_mul_f32 v[130:131], v[20:21], v[34:35] op_sel_hi:[1,0]
	v_pk_mul_f32 v[132:133], v[22:23], v[34:35] op_sel_hi:[1,0]
	v_pk_mul_f32 v[130:131], v[100:101], v[130:131]
	v_pk_mul_f32 v[132:133], v[102:103], v[132:133]
	global_store_dwordx4 v156, v[130:133], s[56:57] offset:1024
	v_pk_mul_f32 v[134:135], v[24:25], v[34:35] op_sel_hi:[1,0]
	v_pk_mul_f32 v[136:137], v[26:27], v[34:35] op_sel_hi:[1,0]
	v_pk_mul_f32 v[134:135], v[104:105], v[134:135]
	v_pk_mul_f32 v[136:137], v[106:107], v[136:137]
	global_store_dwordx4 v156, v[134:137], s[56:57] offset:2048
	v_pk_mul_f32 v[138:139], v[28:29], v[34:35] op_sel_hi:[1,0]
	v_pk_mul_f32 v[140:141], v[30:31], v[34:35] op_sel_hi:[1,0]
	v_pk_mul_f32 v[138:139], v[108:109], v[138:139]
	v_pk_mul_f32 v[140:141], v[110:111], v[140:141]
	global_store_dwordx4 v156, v[138:141], s[56:57] offset:3072
	s_add_i32 s13, s8, s60
	s_lshl_b32 s13, s13, 12
	s_add_u32 s56, s6, s13
	s_addc_u32 s57, s7, 0
	s_add_i32 s8, s8, s24
	global_load_dwordx4 v[16:19], v156, s[56:57]
	global_load_dwordx4 v[20:23], v156, s[56:57] offset:1024
	global_load_dwordx4 v[24:27], v156, s[56:57] offset:2048
	global_load_dwordx4 v[28:31], v156, s[56:57] offset:3072
	s_waitcnt vmcnt(8)
	v_mov_b32_e32 v116, v1
	v_mov_b32_e32 v117, v5
	v_mov_b32_e32 v114, v0
	v_mov_b32_e32 v115, v4
	v_mov_b32_e32 v124, v9
	v_mov_b32_e32 v125, v13
	v_pk_mul_f32 v[116:117], v[116:117], v[116:117]
	v_mov_b32_e32 v32, v2
	v_mov_b32_e32 v33, v6
	v_mov_b32_e32 v122, v8
	v_mov_b32_e32 v123, v12
	v_pk_mul_f32 v[124:125], v[124:125], v[124:125]
	v_pk_fma_f32 v[114:115], v[114:115], v[114:115], v[116:117]
	v_mov_b32_e32 v112, v3
	v_mov_b32_e32 v113, v7
	v_mov_b32_e32 v118, v10
	v_mov_b32_e32 v119, v14
	v_pk_fma_f32 v[116:117], v[122:123], v[122:123], v[124:125]
	v_pk_fma_f32 v[32:33], v[32:33], v[32:33], v[114:115]
	v_mov_b32_e32 v120, v11
	v_mov_b32_e32 v121, v15
	v_pk_fma_f32 v[114:115], v[118:119], v[118:119], v[116:117]
	v_pk_fma_f32 v[32:33], v[112:113], v[112:113], v[32:33]
	v_pk_fma_f32 v[112:113], v[120:121], v[120:121], v[114:115]
	v_add_f32_e32 v32, v32, v33
	v_add_f32_e32 v32, v32, v112
	v_add_f32_e32 v32, v32, v113
	ds_bpermute_b32 v33, v64, v32
	s_waitcnt lgkmcnt(0)
	v_add_f32_e32 v32, v32, v33
	ds_bpermute_b32 v33, v65, v32
	s_waitcnt lgkmcnt(0)
	v_add_f32_e32 v32, v32, v33
	ds_bpermute_b32 v33, v66, v32
	s_waitcnt lgkmcnt(0)
	v_add_f32_e32 v32, v32, v33
	ds_bpermute_b32 v33, v67, v32
	s_waitcnt lgkmcnt(0)
	v_add_f32_e32 v32, v32, v33
	ds_bpermute_b32 v33, v68, v32
	s_waitcnt lgkmcnt(0)
	v_add_f32_e32 v32, v32, v33
	ds_bpermute_b32 v33, v69, v32
	s_waitcnt lgkmcnt(0)
	v_add_f32_e32 v32, v32, v33
	v_fmamk_f32 v32, v32, 0x3a800000, v196
	v_cmp_gt_f32_e32 vcc, s11, v32
	v_mul_f32_e32 v33, 0x4b800000, v32
	s_nop 1
	v_cndmask_b32_e32 v32, v32, v33, vcc
	v_rsq_f32_e32 v34, v32
	s_nop 0
	v_mul_f32_e32 v33, 0x45800000, v34
	v_cndmask_b32_e32 v34, v34, v33, vcc
	v_pk_mul_f32 v[126:127], v[0:1], v[34:35] op_sel_hi:[1,0]
	v_pk_mul_f32 v[128:129], v[2:3], v[34:35] op_sel_hi:[1,0]
	v_pk_mul_f32 v[126:127], v[96:97], v[126:127]
	v_pk_mul_f32 v[128:129], v[98:99], v[128:129]
	global_store_dwordx4 v156, v[126:129], s[62:63]
	v_pk_mul_f32 v[130:131], v[4:5], v[34:35] op_sel_hi:[1,0]
	v_pk_mul_f32 v[132:133], v[6:7], v[34:35] op_sel_hi:[1,0]
	v_pk_mul_f32 v[130:131], v[100:101], v[130:131]
	v_pk_mul_f32 v[132:133], v[102:103], v[132:133]
	global_store_dwordx4 v156, v[130:133], s[62:63] offset:1024
	v_pk_mul_f32 v[134:135], v[8:9], v[34:35] op_sel_hi:[1,0]
	v_pk_mul_f32 v[136:137], v[10:11], v[34:35] op_sel_hi:[1,0]
	v_pk_mul_f32 v[134:135], v[104:105], v[134:135]
	v_pk_mul_f32 v[136:137], v[106:107], v[136:137]
	global_store_dwordx4 v156, v[134:137], s[62:63] offset:2048
	v_pk_mul_f32 v[138:139], v[12:13], v[34:35] op_sel_hi:[1,0]
	v_pk_mul_f32 v[140:141], v[14:15], v[34:35] op_sel_hi:[1,0]
	v_pk_mul_f32 v[138:139], v[108:109], v[138:139]
	v_pk_mul_f32 v[140:141], v[110:111], v[140:141]
	global_store_dwordx4 v156, v[138:141], s[62:63] offset:3072
	s_add_i32 s15, s15, -1
	s_cmp_lg_u32 s15, 0
	s_cbranch_scc1 .Lfn_loop
; DEV void final_norm_item(const Params& p, int g, int item, int tid) {
;   const int wid = tid >> 6, lane = tid & 63;
;   const int r = item * 8 + wid;
;   float* row = p.out + ((long)g * G * SEQ + r) * D;
;   float4 v[4];
;   float ss = 0.f;
; #pragma unroll
;   for (int i = 0; i < 4; ++i) {
;     v[i] = *(const float4*)(row + i * 256 + lane * 4);
;     ss += v[i].x * v[i].x + v[i].y * v[i].y + v[i].z * v[i].z + v[i].w * v[i].w;
;   }
;   ss = wsum(ss, lane);
;   const float rstd = rsqrtf(ss * (1.f / D) + 1e-6f);
; #pragma unroll
;   for (int i = 0; i < 4; ++i) {
;     int col = i * 256 + lane * 4;
;     float4 gg = *(const float4*)(p.final_g + col);
;     float4 o = make_float4(v[i].x * rstd * gg.x, v[i].y * rstd * gg.y, v[i].z * rstd * gg.z, v[i].w * rstd * gg.w);
;     *(float4*)(row + col) = o;
;   }
; }
	s_waitcnt vmcnt(4)
	v_mov_b32_e32 v116, v17
	v_mov_b32_e32 v117, v21
	v_mov_b32_e32 v114, v16
	v_mov_b32_e32 v115, v20
	v_mov_b32_e32 v124, v25
	v_mov_b32_e32 v125, v29
	v_pk_mul_f32 v[116:117], v[116:117], v[116:117]
	v_mov_b32_e32 v32, v18
	v_mov_b32_e32 v33, v22
	v_mov_b32_e32 v122, v24
	v_mov_b32_e32 v123, v28
	v_pk_mul_f32 v[124:125], v[124:125], v[124:125]
	v_pk_fma_f32 v[114:115], v[114:115], v[114:115], v[116:117]
	v_mov_b32_e32 v112, v19
	v_mov_b32_e32 v113, v23
	v_mov_b32_e32 v118, v26
	v_mov_b32_e32 v119, v30
	v_pk_fma_f32 v[116:117], v[122:123], v[122:123], v[124:125]
	v_pk_fma_f32 v[32:33], v[32:33], v[32:33], v[114:115]
	v_mov_b32_e32 v120, v27
	v_mov_b32_e32 v121, v31
	v_pk_fma_f32 v[114:115], v[118:119], v[118:119], v[116:117]
	v_pk_fma_f32 v[32:33], v[112:113], v[112:113], v[32:33]
	v_pk_fma_f32 v[112:113], v[120:121], v[120:121], v[114:115]
	v_add_f32_e32 v32, v32, v33
	v_add_f32_e32 v32, v32, v112
	v_add_f32_e32 v32, v32, v113
	ds_bpermute_b32 v33, v64, v32
	s_waitcnt lgkmcnt(0)
	v_add_f32_e32 v32, v32, v33
	ds_bpermute_b32 v33, v65, v32
	s_waitcnt lgkmcnt(0)
	v_add_f32_e32 v32, v32, v33
	ds_bpermute_b32 v33, v66, v32
	s_waitcnt lgkmcnt(0)
	v_add_f32_e32 v32, v32, v33
	ds_bpermute_b32 v33, v67, v32
	s_waitcnt lgkmcnt(0)
	v_add_f32_e32 v32, v32, v33
	ds_bpermute_b32 v33, v68, v32
	s_waitcnt lgkmcnt(0)
	v_add_f32_e32 v32, v32, v33
	ds_bpermute_b32 v33, v69, v32
	s_waitcnt lgkmcnt(0)
	v_add_f32_e32 v32, v32, v33
	v_fmamk_f32 v32, v32, 0x3a800000, v196
	v_cmp_gt_f32_e32 vcc, s11, v32
	v_mul_f32_e32 v33, 0x4b800000, v32
	s_nop 1
	v_cndmask_b32_e32 v32, v32, v33, vcc
	v_rsq_f32_e32 v34, v32
	s_nop 0
	v_mul_f32_e32 v33, 0x45800000, v34
	v_cndmask_b32_e32 v34, v34, v33, vcc
	v_pk_mul_f32 v[126:127], v[16:17], v[34:35] op_sel_hi:[1,0]
	v_pk_mul_f32 v[128:129], v[18:19], v[34:35] op_sel_hi:[1,0]
	v_pk_mul_f32 v[126:127], v[96:97], v[126:127]
	v_pk_mul_f32 v[128:129], v[98:99], v[128:129]
	global_store_dwordx4 v156, v[126:129], s[56:57]
	v_pk_mul_f32 v[130:131], v[20:21], v[34:35] op_sel_hi:[1,0]
	v_pk_mul_f32 v[132:133], v[22:23], v[34:35] op_sel_hi:[1,0]
	v_pk_mul_f32 v[130:131], v[100:101], v[130:131]
	v_pk_mul_f32 v[132:133], v[102:103], v[132:133]
	global_store_dwordx4 v156, v[130:133], s[56:57] offset:1024
	v_pk_mul_f32 v[134:135], v[24:25], v[34:35] op_sel_hi:[1,0]
	v_pk_mul_f32 v[136:137], v[26:27], v[34:35] op_sel_hi:[1,0]
	v_pk_mul_f32 v[134:135], v[104:105], v[134:135]
	v_pk_mul_f32 v[136:137], v[106:107], v[136:137]
	global_store_dwordx4 v156, v[134:137], s[56:57] offset:2048
	v_pk_mul_f32 v[138:139], v[28:29], v[34:35] op_sel_hi:[1,0]
	v_pk_mul_f32 v[140:141], v[30:31], v[34:35] op_sel_hi:[1,0]
	v_pk_mul_f32 v[138:139], v[108:109], v[138:139]
	v_pk_mul_f32 v[140:141], v[110:111], v[140:141]
	global_store_dwordx4 v156, v[138:141], s[56:57] offset:3072
	s_branch .LBB0_100
.Lfn_generic:
	v_readlane_b32 s8, v254, 36
	s_mov_b32 s9, s75
